# norm-phase row sum-of-squares: SLP-packed (v_mov pairs + v_pk_mul/v_pk_fma) rewritten as plain v_mul/v_fma on the original registers, operand copies removed (bit-identical, ~24 fewer VALU per row)
# speedup vs baseline: 1.0059x; 1.0059x over previous
.LBB0_99:
	s_or_b64 exec, exec, s[8:9]
	s_waitcnt vmcnt(7)
	s_waitcnt vmcnt(6)
	v_mul_f32_e32 v50, v37, v37
	v_mul_f32_e32 v51, v33, v33
	s_waitcnt vmcnt(5)
	v_fma_f32 v48, v36, v36, v50
	v_fma_f32 v49, v32, v32, v51
	v_fma_f32 v48, v38, v38, v48
	v_fma_f32 v49, v34, v34, v49
	s_waitcnt vmcnt(4)
	v_fma_f32 v48, v39, v39, v48
	v_fma_f32 v49, v35, v35, v49
	v_mul_f32_e32 v52, v29, v29
	v_mul_f32_e32 v53, v25, v25
	v_add_f32_e32 v48, v48, v49
	v_fma_f32 v50, v28, v28, v52
	v_fma_f32 v51, v24, v24, v53
	v_fma_f32 v50, v30, v30, v50
	v_fma_f32 v51, v26, v26, v51
	v_fma_f32 v50, v31, v31, v50
	v_fma_f32 v51, v27, v27, v51
	v_ashrrev_i32_e32 v163, 31, v162
	v_add_f32_e32 v48, v48, v50
	v_add_f32_e32 v48, v48, v51
	ds_bpermute_b32 v49, v178, v48
	v_lshlrev_b64 v[52:53], 11, v[162:163]
	v_lshl_add_u64 v[52:53], v[148:149], 0, v[52:53]
	s_waitcnt lgkmcnt(0)
	v_add_f32_e32 v48, v48, v49
	ds_bpermute_b32 v49, v179, v48
	s_waitcnt lgkmcnt(0)
	v_add_f32_e32 v48, v48, v49
	s_nop 1
	v_add_f32_dpp v48, v48, v48 row_ror:8 row_mask:0xf bank_mask:0xf
	s_nop 1
	v_add_f32_dpp v48, v48, v48 row_ror:4 row_mask:0xf bank_mask:0xf
	s_nop 1
	v_add_f32_dpp v50, v48, v48 quad_perm:[2,3,0,1] row_mask:0xf bank_mask:0xf
	v_pk_add_f32 v[48:49], v[22:23], 1.0 op_sel_hi:[1,0]
	s_nop 1
	v_add_f32_dpp v50, v50, v50 quad_perm:[1,0,3,2] row_mask:0xf bank_mask:0xf
	v_fmamk_f32 v50, v50, 0x3a800000, v184
	v_rsq_f32_e32 v54, v50
	v_pk_add_f32 v[50:51], v[20:21], 1.0 op_sel_hi:[1,0]
	v_pk_mul_f32 v[38:39], v[38:39], v[54:55] op_sel_hi:[1,0]
	v_pk_mul_f32 v[36:37], v[36:37], v[54:55] op_sel_hi:[1,0]
	v_pk_mul_f32 v[38:39], v[2:3], v[38:39]
	v_pk_mul_f32 v[36:37], v[0:1], v[36:37]
	v_pk_fma_f32 v[38:39], v[48:49], v[38:39], v[18:19]
	v_pk_fma_f32 v[36:37], v[50:51], v[36:37], v[16:17]
	v_pk_mul_f32 v[34:35], v[34:35], v[54:55] op_sel_hi:[1,0]
	v_cvt_pk_bf16_f32 v36, v36, v37
	v_cvt_pk_bf16_f32 v37, v38, v39
	v_pk_mul_f32 v[32:33], v[32:33], v[54:55] op_sel_hi:[1,0]
	global_store_dwordx2 v[52:53], v[36:37], off
	v_pk_mul_f32 v[32:33], v[4:5], v[32:33]
	v_pk_mul_f32 v[34:35], v[6:7], v[34:35]
	v_pk_add_f32 v[36:37], v[46:47], 1.0 op_sel_hi:[1,0]
	v_pk_add_f32 v[38:39], v[44:45], 1.0 op_sel_hi:[1,0]
	v_pk_fma_f32 v[34:35], v[36:37], v[34:35], v[42:43]
	v_pk_fma_f32 v[32:33], v[38:39], v[32:33], v[40:41]
	v_pk_mul_f32 v[30:31], v[30:31], v[54:55] op_sel_hi:[1,0]
	v_cvt_pk_bf16_f32 v32, v32, v33
	v_cvt_pk_bf16_f32 v33, v34, v35
	v_pk_mul_f32 v[28:29], v[28:29], v[54:55] op_sel_hi:[1,0]
	global_store_dwordx2 v[52:53], v[32:33], off offset:512
	v_pk_mul_f32 v[28:29], v[8:9], v[28:29]
	v_pk_mul_f32 v[30:31], v[10:11], v[30:31]
	v_pk_add_f32 v[32:33], v[70:71], 1.0 op_sel_hi:[1,0]
	v_pk_add_f32 v[34:35], v[68:69], 1.0 op_sel_hi:[1,0]
	v_pk_fma_f32 v[30:31], v[32:33], v[30:31], v[66:67]
	v_pk_fma_f32 v[28:29], v[34:35], v[28:29], v[64:65]
	v_pk_mul_f32 v[26:27], v[26:27], v[54:55] op_sel_hi:[1,0]
	v_cvt_pk_bf16_f32 v28, v28, v29
	v_cvt_pk_bf16_f32 v29, v30, v31
	v_pk_mul_f32 v[24:25], v[24:25], v[54:55] op_sel_hi:[1,0]
	global_store_dwordx2 v[52:53], v[28:29], off offset:1024
	v_pk_mul_f32 v[24:25], v[12:13], v[24:25]
	v_pk_mul_f32 v[26:27], v[14:15], v[26:27]
	v_pk_add_f32 v[28:29], v[94:95], 1.0 op_sel_hi:[1,0]
	v_pk_add_f32 v[30:31], v[92:93], 1.0 op_sel_hi:[1,0]
	v_pk_fma_f32 v[26:27], v[28:29], v[26:27], v[90:91]
	v_pk_fma_f32 v[24:25], v[30:31], v[24:25], v[88:89]
	s_nop 0
	v_cvt_pk_bf16_f32 v24, v24, v25
	v_cvt_pk_bf16_f32 v25, v26, v27
	global_store_dwordx2 v[52:53], v[24:25], off offset:1536

.LBB0_111:
	s_or_b64 exec, exec, s[6:7]
	s_waitcnt vmcnt(23)
	s_waitcnt vmcnt(22)
	v_mul_f32_e32 v174, v141, v141
	v_mul_f32_e32 v175, v137, v137
	s_waitcnt vmcnt(21)
	v_fma_f32 v172, v140, v140, v174
	v_fma_f32 v173, v136, v136, v175
	v_fma_f32 v172, v142, v142, v172
	v_fma_f32 v173, v138, v138, v173
	s_waitcnt vmcnt(20)
	v_fma_f32 v172, v143, v143, v172
	v_fma_f32 v173, v139, v139, v173
	v_mul_f32_e32 v186, v133, v133
	v_mul_f32_e32 v187, v129, v129
	v_add_f32_e32 v145, v172, v173
	v_fma_f32 v174, v132, v132, v186
	v_fma_f32 v175, v128, v128, v187
	v_fma_f32 v174, v134, v134, v174
	v_fma_f32 v175, v130, v130, v175
	v_fma_f32 v174, v135, v135, v174
	v_fma_f32 v175, v131, v131, v175
	v_pk_add_f32 v[172:173], v[22:23], 1.0 op_sel_hi:[1,0]
	v_add_f32_e32 v145, v145, v174
	v_add_f32_e32 v145, v145, v175
	ds_bpermute_b32 v163, v178, v145
	v_pk_add_f32 v[174:175], v[20:21], 1.0 op_sel_hi:[1,0]
	s_waitcnt lgkmcnt(0)
	v_add_f32_e32 v145, v145, v163
	ds_bpermute_b32 v163, v179, v145
	s_waitcnt lgkmcnt(0)
	v_add_f32_e32 v145, v145, v163
	s_nop 1
	v_add_f32_dpp v145, v145, v145 row_ror:8 row_mask:0xf bank_mask:0xf
	s_nop 1
	v_add_f32_dpp v145, v145, v145 row_ror:4 row_mask:0xf bank_mask:0xf
	s_nop 1
	v_add_f32_dpp v163, v145, v145 quad_perm:[2,3,0,1] row_mask:0xf bank_mask:0xf
	v_ashrrev_i32_e32 v145, 31, v144
	v_lshlrev_b64 v[186:187], 11, v[144:145]
	v_lshl_add_u64 v[186:187], v[148:149], 0, v[186:187]
	s_nop 1
	v_add_f32_dpp v163, v163, v163 quad_perm:[1,0,3,2] row_mask:0xf bank_mask:0xf
	v_fmamk_f32 v163, v163, 0x3a800000, v184
	v_rsq_f32_e32 v163, v163
	s_nop 0
	v_mov_b32_e32 v188, v163
	v_pk_mul_f32 v[142:143], v[142:143], v[188:189] op_sel_hi:[1,0]
	v_pk_mul_f32 v[140:141], v[140:141], v[188:189] op_sel_hi:[1,0]
	v_pk_mul_f32 v[142:143], v[2:3], v[142:143]
	v_pk_mul_f32 v[140:141], v[0:1], v[140:141]
	v_pk_fma_f32 v[142:143], v[172:173], v[142:143], v[18:19]
	v_pk_fma_f32 v[140:141], v[174:175], v[140:141], v[16:17]
	v_pk_mul_f32 v[138:139], v[138:139], v[188:189] op_sel_hi:[1,0]
	v_cvt_pk_bf16_f32 v140, v140, v141
	v_cvt_pk_bf16_f32 v141, v142, v143
	v_pk_mul_f32 v[136:137], v[136:137], v[188:189] op_sel_hi:[1,0]
	global_store_dwordx2 v[186:187], v[140:141], off
	v_pk_mul_f32 v[140:141], v[4:5], v[136:137]
	v_pk_mul_f32 v[142:143], v[6:7], v[138:139]
	v_pk_add_f32 v[136:137], v[46:47], 1.0 op_sel_hi:[1,0]
	v_pk_add_f32 v[138:139], v[44:45], 1.0 op_sel_hi:[1,0]
	v_pk_fma_f32 v[142:143], v[136:137], v[142:143], v[42:43]
	v_pk_fma_f32 v[140:141], v[138:139], v[140:141], v[40:41]
	v_pk_mul_f32 v[134:135], v[134:135], v[188:189] op_sel_hi:[1,0]
	v_cvt_pk_bf16_f32 v140, v140, v141
	v_cvt_pk_bf16_f32 v141, v142, v143
	v_pk_mul_f32 v[132:133], v[132:133], v[188:189] op_sel_hi:[1,0]
	global_store_dwordx2 v[186:187], v[140:141], off offset:512
	v_pk_mul_f32 v[140:141], v[8:9], v[132:133]
	v_pk_mul_f32 v[142:143], v[10:11], v[134:135]
	v_pk_add_f32 v[132:133], v[70:71], 1.0 op_sel_hi:[1,0]
	v_pk_add_f32 v[134:135], v[68:69], 1.0 op_sel_hi:[1,0]
	v_pk_fma_f32 v[142:143], v[132:133], v[142:143], v[66:67]
	v_pk_fma_f32 v[140:141], v[134:135], v[140:141], v[64:65]
	v_pk_mul_f32 v[130:131], v[130:131], v[188:189] op_sel_hi:[1,0]
	v_cvt_pk_bf16_f32 v140, v140, v141
	v_cvt_pk_bf16_f32 v141, v142, v143
	v_pk_mul_f32 v[128:129], v[128:129], v[188:189] op_sel_hi:[1,0]
	global_store_dwordx2 v[186:187], v[140:141], off offset:1024
	v_pk_mul_f32 v[140:141], v[12:13], v[128:129]
	v_pk_mul_f32 v[142:143], v[14:15], v[130:131]
	v_pk_add_f32 v[128:129], v[94:95], 1.0 op_sel_hi:[1,0]
	v_pk_add_f32 v[130:131], v[92:93], 1.0 op_sel_hi:[1,0]
	v_pk_fma_f32 v[142:143], v[128:129], v[142:143], v[90:91]
	v_pk_fma_f32 v[140:141], v[130:131], v[140:141], v[88:89]
	v_cmp_lt_i32_e32 vcc, v170, v176
	v_cvt_pk_bf16_f32 v140, v140, v141
	v_cvt_pk_bf16_f32 v141, v142, v143
	global_store_dwordx2 v[186:187], v[140:141], off offset:1536
	s_and_saveexec_b64 s[6:7], vcc
	s_cbranch_execz .LBB0_136
	v_add_u32_e32 v140, 0xffffe001, v144
	v_ashrrev_i32_e32 v140, 10, v140
	v_add_u32_e32 v140, 1, v140
	v_cmp_lt_i32_e32 vcc, s15, v144
	s_nop 1
	v_cndmask_b32_e32 v140, 0, v140, vcc
	v_cmp_ne_u32_e32 vcc, v140, v185
	s_and_saveexec_b64 s[8:9], vcc
	s_cbranch_execz .LBB0_122
	global_load_dwordx4 v[16:19], v[150:151], off
	global_load_dwordx4 v[20:23], v[152:153], off
	v_mad_i64_i32 v[128:129], s[10:11], v140, s3, v[160:161]
	s_mov_b64 s[10:11], 0

.LBB0_122:
	s_or_b64 exec, exec, s[8:9]
	s_waitcnt vmcnt(23)
	s_waitcnt vmcnt(22)
	v_mul_f32_e32 v142, v125, v125
	v_mul_f32_e32 v143, v121, v121
	s_waitcnt vmcnt(21)
	v_fma_f32 v140, v124, v124, v142
	v_fma_f32 v141, v120, v120, v143
	v_fma_f32 v140, v126, v126, v140
	v_fma_f32 v141, v122, v122, v141
	s_waitcnt vmcnt(20)
	v_fma_f32 v140, v127, v127, v140
	v_fma_f32 v141, v123, v123, v141
	v_mul_f32_e32 v186, v117, v117
	v_mul_f32_e32 v187, v113, v113
	v_add_f32_e32 v140, v140, v141
	v_fma_f32 v142, v116, v116, v186
	v_fma_f32 v143, v112, v112, v187
	v_fma_f32 v142, v118, v118, v142
	v_fma_f32 v143, v114, v114, v143
	v_mov_b32_e32 v186, v119
	v_mov_b32_e32 v187, v115
	v_fma_f32 v142, v119, v119, v142
	v_fma_f32 v143, v115, v115, v143
	v_ashrrev_i32_e32 v171, 31, v170
	v_add_f32_e32 v140, v140, v142
	v_add_f32_e32 v140, v140, v143
	ds_bpermute_b32 v141, v178, v140
	s_waitcnt lgkmcnt(0)
	v_add_f32_e32 v140, v140, v141
	ds_bpermute_b32 v141, v179, v140
	s_waitcnt lgkmcnt(0)
	v_add_f32_e32 v140, v140, v141
	s_nop 1
	v_add_f32_dpp v140, v140, v140 row_ror:8 row_mask:0xf bank_mask:0xf
	s_nop 1
	v_add_f32_dpp v140, v140, v140 row_ror:4 row_mask:0xf bank_mask:0xf
	s_nop 1
	v_add_f32_dpp v140, v140, v140 quad_perm:[2,3,0,1] row_mask:0xf bank_mask:0xf
	s_nop 1
	v_add_f32_dpp v140, v140, v140 quad_perm:[1,0,3,2] row_mask:0xf bank_mask:0xf
	v_fmamk_f32 v140, v140, 0x3a800000, v184
	v_rsq_f32_e32 v142, v140
	v_lshlrev_b64 v[140:141], 11, v[170:171]
	v_lshl_add_u64 v[140:141], v[148:149], 0, v[140:141]
	v_pk_mul_f32 v[126:127], v[126:127], v[142:143] op_sel_hi:[1,0]
	v_pk_mul_f32 v[124:125], v[124:125], v[142:143] op_sel_hi:[1,0]
	v_pk_mul_f32 v[122:123], v[122:123], v[142:143] op_sel_hi:[1,0]
	v_pk_mul_f32 v[120:121], v[120:121], v[142:143] op_sel_hi:[1,0]
	v_pk_mul_f32 v[118:119], v[118:119], v[142:143] op_sel_hi:[1,0]
	v_pk_mul_f32 v[116:117], v[116:117], v[142:143] op_sel_hi:[1,0]
	v_pk_mul_f32 v[114:115], v[114:115], v[142:143] op_sel_hi:[1,0]
	v_pk_mul_f32 v[112:113], v[112:113], v[142:143] op_sel_hi:[1,0]
	v_pk_mul_f32 v[124:125], v[0:1], v[124:125]
	v_pk_mul_f32 v[126:127], v[2:3], v[126:127]
	v_pk_mul_f32 v[120:121], v[4:5], v[120:121]
	v_pk_mul_f32 v[122:123], v[6:7], v[122:123]
	v_pk_mul_f32 v[116:117], v[8:9], v[116:117]
	v_pk_mul_f32 v[118:119], v[10:11], v[118:119]
	v_pk_mul_f32 v[112:113], v[12:13], v[112:113]
	v_pk_mul_f32 v[114:115], v[14:15], v[114:115]
	v_pk_fma_f32 v[126:127], v[172:173], v[126:127], v[18:19]
	v_pk_fma_f32 v[124:125], v[174:175], v[124:125], v[16:17]
	v_pk_fma_f32 v[122:123], v[136:137], v[122:123], v[42:43]
	v_pk_fma_f32 v[120:121], v[138:139], v[120:121], v[40:41]
	v_pk_fma_f32 v[118:119], v[132:133], v[118:119], v[66:67]
	v_pk_fma_f32 v[116:117], v[134:135], v[116:117], v[64:65]
	v_pk_fma_f32 v[114:115], v[128:129], v[114:115], v[90:91]
	v_pk_fma_f32 v[112:113], v[130:131], v[112:113], v[88:89]
	v_cvt_pk_bf16_f32 v124, v124, v125
	v_cvt_pk_bf16_f32 v125, v126, v127
	v_cvt_pk_bf16_f32 v120, v120, v121
	v_cvt_pk_bf16_f32 v121, v122, v123
	v_cvt_pk_bf16_f32 v116, v116, v117
	v_cvt_pk_bf16_f32 v117, v118, v119
	v_cvt_pk_bf16_f32 v112, v112, v113
	v_cvt_pk_bf16_f32 v113, v114, v115
	global_store_dwordx2 v[140:141], v[124:125], off
	global_store_dwordx2 v[140:141], v[120:121], off offset:512
	global_store_dwordx2 v[140:141], v[116:117], off offset:1024
	global_store_dwordx2 v[140:141], v[112:113], off offset:1536
	s_or_b64 exec, exec, s[6:7]
	v_cmp_lt_i32_e32 vcc, v168, v176
	s_and_saveexec_b64 s[6:7], vcc
	s_cbranch_execnz .LBB0_137

.LBB0_134:
	s_or_b64 exec, exec, s[8:9]
	s_waitcnt vmcnt(15)
	s_waitcnt vmcnt(14)
	v_mul_f32_e32 v98, v85, v85
	v_mul_f32_e32 v99, v81, v81
	s_waitcnt vmcnt(13)
	v_fma_f32 v96, v84, v84, v98
	v_fma_f32 v97, v80, v80, v99
	v_fma_f32 v96, v86, v86, v96
	v_fma_f32 v97, v82, v82, v97
	s_waitcnt vmcnt(12)
	v_fma_f32 v96, v87, v87, v96
	v_fma_f32 v97, v83, v83, v97
	v_mul_f32_e32 v100, v77, v77
	v_mul_f32_e32 v101, v73, v73
	v_add_f32_e32 v96, v96, v97
	v_fma_f32 v98, v76, v76, v100
	v_fma_f32 v99, v72, v72, v101
	v_fma_f32 v98, v78, v78, v98
	v_fma_f32 v99, v74, v74, v99
	v_fma_f32 v98, v79, v79, v98
	v_fma_f32 v99, v75, v75, v99
	v_ashrrev_i32_e32 v167, 31, v166
	v_add_f32_e32 v96, v96, v98
	v_add_f32_e32 v96, v96, v99
	ds_bpermute_b32 v97, v178, v96
	v_lshlrev_b64 v[100:101], 11, v[166:167]
	v_lshl_add_u64 v[100:101], v[148:149], 0, v[100:101]
	s_waitcnt lgkmcnt(0)
	v_add_f32_e32 v96, v96, v97
	ds_bpermute_b32 v97, v179, v96
	s_waitcnt lgkmcnt(0)
	v_add_f32_e32 v96, v96, v97
	s_nop 1
	v_add_f32_dpp v96, v96, v96 row_ror:8 row_mask:0xf bank_mask:0xf
	s_nop 1
	v_add_f32_dpp v96, v96, v96 row_ror:4 row_mask:0xf bank_mask:0xf
	s_nop 1
	v_add_f32_dpp v98, v96, v96 quad_perm:[2,3,0,1] row_mask:0xf bank_mask:0xf
	v_pk_add_f32 v[96:97], v[22:23], 1.0 op_sel_hi:[1,0]
	s_nop 1
	v_add_f32_dpp v98, v98, v98 quad_perm:[1,0,3,2] row_mask:0xf bank_mask:0xf
	v_fmamk_f32 v98, v98, 0x3a800000, v184
	v_rsq_f32_e32 v102, v98
	v_pk_add_f32 v[98:99], v[20:21], 1.0 op_sel_hi:[1,0]
	v_pk_mul_f32 v[86:87], v[86:87], v[102:103] op_sel_hi:[1,0]
	v_pk_mul_f32 v[84:85], v[84:85], v[102:103] op_sel_hi:[1,0]
	v_pk_mul_f32 v[86:87], v[2:3], v[86:87]
	v_pk_mul_f32 v[84:85], v[0:1], v[84:85]
	v_pk_fma_f32 v[86:87], v[96:97], v[86:87], v[18:19]
	v_pk_fma_f32 v[84:85], v[98:99], v[84:85], v[16:17]
	v_pk_mul_f32 v[82:83], v[82:83], v[102:103] op_sel_hi:[1,0]
	v_cvt_pk_bf16_f32 v84, v84, v85
	v_cvt_pk_bf16_f32 v85, v86, v87
	v_pk_mul_f32 v[80:81], v[80:81], v[102:103] op_sel_hi:[1,0]
	global_store_dwordx2 v[100:101], v[84:85], off
	v_pk_mul_f32 v[80:81], v[4:5], v[80:81]
	v_pk_mul_f32 v[82:83], v[6:7], v[82:83]
	v_pk_add_f32 v[84:85], v[46:47], 1.0 op_sel_hi:[1,0]
	v_pk_add_f32 v[86:87], v[44:45], 1.0 op_sel_hi:[1,0]
	v_pk_fma_f32 v[82:83], v[84:85], v[82:83], v[42:43]
	v_pk_fma_f32 v[80:81], v[86:87], v[80:81], v[40:41]
	v_pk_mul_f32 v[78:79], v[78:79], v[102:103] op_sel_hi:[1,0]
	v_cvt_pk_bf16_f32 v80, v80, v81
	v_cvt_pk_bf16_f32 v81, v82, v83
	v_pk_mul_f32 v[76:77], v[76:77], v[102:103] op_sel_hi:[1,0]
	global_store_dwordx2 v[100:101], v[80:81], off offset:512
	v_pk_mul_f32 v[76:77], v[8:9], v[76:77]
	v_pk_mul_f32 v[78:79], v[10:11], v[78:79]
	v_pk_add_f32 v[80:81], v[70:71], 1.0 op_sel_hi:[1,0]
	v_pk_add_f32 v[82:83], v[68:69], 1.0 op_sel_hi:[1,0]
	v_pk_fma_f32 v[78:79], v[80:81], v[78:79], v[66:67]
	v_pk_fma_f32 v[76:77], v[82:83], v[76:77], v[64:65]
	v_pk_mul_f32 v[74:75], v[74:75], v[102:103] op_sel_hi:[1,0]
	v_cvt_pk_bf16_f32 v76, v76, v77
	v_cvt_pk_bf16_f32 v77, v78, v79
	v_pk_mul_f32 v[72:73], v[72:73], v[102:103] op_sel_hi:[1,0]
	global_store_dwordx2 v[100:101], v[76:77], off offset:1024
	v_pk_mul_f32 v[72:73], v[12:13], v[72:73]
	v_pk_mul_f32 v[74:75], v[14:15], v[74:75]
	v_pk_add_f32 v[76:77], v[94:95], 1.0 op_sel_hi:[1,0]
	v_pk_add_f32 v[78:79], v[92:93], 1.0 op_sel_hi:[1,0]
	v_pk_fma_f32 v[74:75], v[76:77], v[74:75], v[90:91]
	v_pk_fma_f32 v[72:73], v[78:79], v[72:73], v[88:89]
	s_nop 0
	v_cvt_pk_bf16_f32 v72, v72, v73
	v_cvt_pk_bf16_f32 v73, v74, v75
	global_store_dwordx2 v[100:101], v[72:73], off offset:1536
	s_or_b64 exec, exec, s[6:7]
	v_cmp_lt_i32_e32 vcc, v164, v176
	s_and_saveexec_b64 s[6:7], vcc
	s_cbranch_execnz .LBB0_149

.LBB0_147:
	s_or_b64 exec, exec, s[8:9]
	s_waitcnt vmcnt(19)
	s_waitcnt vmcnt(18)
	v_mul_f32_e32 v114, v109, v109
	v_mul_f32_e32 v115, v105, v105
	s_waitcnt vmcnt(17)
	v_fma_f32 v112, v108, v108, v114
	v_fma_f32 v113, v104, v104, v115
	v_fma_f32 v112, v110, v110, v112
	v_fma_f32 v113, v106, v106, v113
	s_waitcnt vmcnt(16)
	v_fma_f32 v112, v111, v111, v112
	v_fma_f32 v113, v107, v107, v113
	v_mul_f32_e32 v116, v101, v101
	v_mul_f32_e32 v117, v97, v97
	v_add_f32_e32 v112, v112, v113
	v_fma_f32 v114, v100, v100, v116
	v_fma_f32 v115, v96, v96, v117
	v_fma_f32 v114, v102, v102, v114
	v_fma_f32 v115, v98, v98, v115
	v_fma_f32 v114, v103, v103, v114
	v_fma_f32 v115, v99, v99, v115
	v_ashrrev_i32_e32 v169, 31, v168
	v_add_f32_e32 v112, v112, v114
	v_add_f32_e32 v112, v112, v115
	ds_bpermute_b32 v113, v178, v112
	v_lshlrev_b64 v[116:117], 11, v[168:169]
	v_lshl_add_u64 v[116:117], v[148:149], 0, v[116:117]
	s_waitcnt lgkmcnt(0)
	v_add_f32_e32 v112, v112, v113
	ds_bpermute_b32 v113, v179, v112
	s_waitcnt lgkmcnt(0)
	v_add_f32_e32 v112, v112, v113
	s_nop 1
	v_add_f32_dpp v112, v112, v112 row_ror:8 row_mask:0xf bank_mask:0xf
	s_nop 1
	v_add_f32_dpp v112, v112, v112 row_ror:4 row_mask:0xf bank_mask:0xf
	s_nop 1
	v_add_f32_dpp v114, v112, v112 quad_perm:[2,3,0,1] row_mask:0xf bank_mask:0xf
	v_pk_add_f32 v[112:113], v[22:23], 1.0 op_sel_hi:[1,0]
	s_nop 1
	v_add_f32_dpp v114, v114, v114 quad_perm:[1,0,3,2] row_mask:0xf bank_mask:0xf
	v_fmamk_f32 v114, v114, 0x3a800000, v184
	v_rsq_f32_e32 v118, v114
	v_pk_add_f32 v[114:115], v[20:21], 1.0 op_sel_hi:[1,0]
	v_pk_mul_f32 v[110:111], v[110:111], v[118:119] op_sel_hi:[1,0]
	v_pk_mul_f32 v[108:109], v[108:109], v[118:119] op_sel_hi:[1,0]
	v_pk_mul_f32 v[110:111], v[2:3], v[110:111]
	v_pk_mul_f32 v[108:109], v[0:1], v[108:109]
	v_pk_fma_f32 v[110:111], v[112:113], v[110:111], v[18:19]
	v_pk_fma_f32 v[108:109], v[114:115], v[108:109], v[16:17]
	v_pk_mul_f32 v[106:107], v[106:107], v[118:119] op_sel_hi:[1,0]
	v_cvt_pk_bf16_f32 v108, v108, v109
	v_cvt_pk_bf16_f32 v109, v110, v111
	v_pk_mul_f32 v[104:105], v[104:105], v[118:119] op_sel_hi:[1,0]
	global_store_dwordx2 v[116:117], v[108:109], off
	v_pk_mul_f32 v[104:105], v[4:5], v[104:105]
	v_pk_mul_f32 v[106:107], v[6:7], v[106:107]
	v_pk_add_f32 v[108:109], v[46:47], 1.0 op_sel_hi:[1,0]
	v_pk_add_f32 v[110:111], v[44:45], 1.0 op_sel_hi:[1,0]
	v_pk_fma_f32 v[106:107], v[108:109], v[106:107], v[42:43]
	v_pk_fma_f32 v[104:105], v[110:111], v[104:105], v[40:41]
	v_pk_mul_f32 v[102:103], v[102:103], v[118:119] op_sel_hi:[1,0]
	v_cvt_pk_bf16_f32 v104, v104, v105
	v_cvt_pk_bf16_f32 v105, v106, v107
	v_pk_mul_f32 v[100:101], v[100:101], v[118:119] op_sel_hi:[1,0]
	global_store_dwordx2 v[116:117], v[104:105], off offset:512
	v_pk_mul_f32 v[100:101], v[8:9], v[100:101]
	v_pk_mul_f32 v[102:103], v[10:11], v[102:103]
	v_pk_add_f32 v[104:105], v[70:71], 1.0 op_sel_hi:[1,0]
	v_pk_add_f32 v[106:107], v[68:69], 1.0 op_sel_hi:[1,0]
	v_pk_fma_f32 v[102:103], v[104:105], v[102:103], v[66:67]
	v_pk_fma_f32 v[100:101], v[106:107], v[100:101], v[64:65]
	v_pk_mul_f32 v[98:99], v[98:99], v[118:119] op_sel_hi:[1,0]
	v_cvt_pk_bf16_f32 v100, v100, v101
	v_cvt_pk_bf16_f32 v101, v102, v103
	v_pk_mul_f32 v[96:97], v[96:97], v[118:119] op_sel_hi:[1,0]
	global_store_dwordx2 v[116:117], v[100:101], off offset:1024
	v_pk_mul_f32 v[96:97], v[12:13], v[96:97]
	v_pk_mul_f32 v[98:99], v[14:15], v[98:99]
	v_pk_add_f32 v[100:101], v[94:95], 1.0 op_sel_hi:[1,0]
	v_pk_add_f32 v[102:103], v[92:93], 1.0 op_sel_hi:[1,0]
	v_pk_fma_f32 v[98:99], v[100:101], v[98:99], v[90:91]
	v_pk_fma_f32 v[96:97], v[102:103], v[96:97], v[88:89]
	s_nop 0
	v_cvt_pk_bf16_f32 v96, v96, v97
	v_cvt_pk_bf16_f32 v97, v98, v99
	global_store_dwordx2 v[116:117], v[96:97], off offset:1536
	s_or_b64 exec, exec, s[6:7]
	v_cmp_lt_i32_e32 vcc, v166, v176
	s_and_saveexec_b64 s[6:7], vcc
	s_cbranch_execnz .LBB0_124

.LBB0_159:
	s_or_b64 exec, exec, s[8:9]
	s_waitcnt vmcnt(11)
	s_waitcnt vmcnt(10)
	v_mul_f32_e32 v74, v61, v61
	v_mul_f32_e32 v75, v57, v57
	s_waitcnt vmcnt(9)
	v_fma_f32 v72, v60, v60, v74
	v_fma_f32 v73, v56, v56, v75
	v_fma_f32 v72, v62, v62, v72
	v_fma_f32 v73, v58, v58, v73
	s_waitcnt vmcnt(8)
	v_fma_f32 v72, v63, v63, v72
	v_fma_f32 v73, v59, v59, v73
	v_mul_f32_e32 v76, v53, v53
	v_mul_f32_e32 v77, v49, v49
	v_add_f32_e32 v72, v72, v73
	v_fma_f32 v74, v52, v52, v76
	v_fma_f32 v75, v48, v48, v77
	v_fma_f32 v74, v54, v54, v74
	v_fma_f32 v75, v50, v50, v75
	v_fma_f32 v74, v55, v55, v74
	v_fma_f32 v75, v51, v51, v75
	v_ashrrev_i32_e32 v165, 31, v164
	v_add_f32_e32 v72, v72, v74
	v_add_f32_e32 v72, v72, v75
	ds_bpermute_b32 v73, v178, v72
	v_lshlrev_b64 v[76:77], 11, v[164:165]
	v_lshl_add_u64 v[76:77], v[148:149], 0, v[76:77]
	s_waitcnt lgkmcnt(0)
	v_add_f32_e32 v72, v72, v73
	ds_bpermute_b32 v73, v179, v72
	s_waitcnt lgkmcnt(0)
	v_add_f32_e32 v72, v72, v73
	s_nop 1
	v_add_f32_dpp v72, v72, v72 row_ror:8 row_mask:0xf bank_mask:0xf
	s_nop 1
	v_add_f32_dpp v72, v72, v72 row_ror:4 row_mask:0xf bank_mask:0xf
	s_nop 1
	v_add_f32_dpp v74, v72, v72 quad_perm:[2,3,0,1] row_mask:0xf bank_mask:0xf
	v_pk_add_f32 v[72:73], v[22:23], 1.0 op_sel_hi:[1,0]
	s_nop 1
	v_add_f32_dpp v74, v74, v74 quad_perm:[1,0,3,2] row_mask:0xf bank_mask:0xf
	v_fmamk_f32 v74, v74, 0x3a800000, v184
	v_rsq_f32_e32 v78, v74
	v_pk_add_f32 v[74:75], v[20:21], 1.0 op_sel_hi:[1,0]
	v_pk_mul_f32 v[62:63], v[62:63], v[78:79] op_sel_hi:[1,0]
	v_pk_mul_f32 v[60:61], v[60:61], v[78:79] op_sel_hi:[1,0]
	v_pk_mul_f32 v[62:63], v[2:3], v[62:63]
	v_pk_mul_f32 v[60:61], v[0:1], v[60:61]
	v_pk_fma_f32 v[62:63], v[72:73], v[62:63], v[18:19]
	v_pk_fma_f32 v[60:61], v[74:75], v[60:61], v[16:17]
	v_pk_mul_f32 v[58:59], v[58:59], v[78:79] op_sel_hi:[1,0]
	v_cvt_pk_bf16_f32 v60, v60, v61
	v_cvt_pk_bf16_f32 v61, v62, v63
	v_pk_mul_f32 v[56:57], v[56:57], v[78:79] op_sel_hi:[1,0]
	global_store_dwordx2 v[76:77], v[60:61], off
	v_pk_mul_f32 v[56:57], v[4:5], v[56:57]
	v_pk_mul_f32 v[58:59], v[6:7], v[58:59]
	v_pk_add_f32 v[60:61], v[46:47], 1.0 op_sel_hi:[1,0]
	v_pk_add_f32 v[62:63], v[44:45], 1.0 op_sel_hi:[1,0]
	v_pk_fma_f32 v[58:59], v[60:61], v[58:59], v[42:43]
	v_pk_fma_f32 v[56:57], v[62:63], v[56:57], v[40:41]
	v_pk_mul_f32 v[54:55], v[54:55], v[78:79] op_sel_hi:[1,0]
	v_cvt_pk_bf16_f32 v56, v56, v57
	v_cvt_pk_bf16_f32 v57, v58, v59
	v_pk_mul_f32 v[52:53], v[52:53], v[78:79] op_sel_hi:[1,0]
	global_store_dwordx2 v[76:77], v[56:57], off offset:512
	v_pk_mul_f32 v[52:53], v[8:9], v[52:53]
	v_pk_mul_f32 v[54:55], v[10:11], v[54:55]
	v_pk_add_f32 v[56:57], v[70:71], 1.0 op_sel_hi:[1,0]
	v_pk_add_f32 v[58:59], v[68:69], 1.0 op_sel_hi:[1,0]
	v_pk_fma_f32 v[54:55], v[56:57], v[54:55], v[66:67]
	v_pk_fma_f32 v[52:53], v[58:59], v[52:53], v[64:65]
	v_pk_mul_f32 v[50:51], v[50:51], v[78:79] op_sel_hi:[1,0]
	v_cvt_pk_bf16_f32 v52, v52, v53
	v_cvt_pk_bf16_f32 v53, v54, v55
	v_pk_mul_f32 v[48:49], v[48:49], v[78:79] op_sel_hi:[1,0]
	global_store_dwordx2 v[76:77], v[52:53], off offset:1024
	v_pk_mul_f32 v[48:49], v[12:13], v[48:49]
	v_pk_mul_f32 v[50:51], v[14:15], v[50:51]
	v_pk_add_f32 v[52:53], v[94:95], 1.0 op_sel_hi:[1,0]
	v_pk_add_f32 v[54:55], v[92:93], 1.0 op_sel_hi:[1,0]
	v_pk_fma_f32 v[50:51], v[52:53], v[50:51], v[90:91]
	v_pk_fma_f32 v[48:49], v[54:55], v[48:49], v[88:89]
	s_nop 0
	v_cvt_pk_bf16_f32 v48, v48, v49
	v_cvt_pk_bf16_f32 v49, v50, v51
	global_store_dwordx2 v[76:77], v[48:49], off offset:1536
	s_or_b64 exec, exec, s[6:7]
	v_cmp_lt_i32_e32 vcc, v162, v176
	s_and_saveexec_b64 s[6:7], vcc
	s_cbranch_execz .LBB0_100

.LBB0_1130:
	s_or_b64 exec, exec, s[40:41]
	v_mul_f32_e32 v60, v45, v45
	v_mul_f32_e32 v61, v41, v41
	v_fma_f32 v58, v44, v44, v60
	v_fma_f32 v59, v40, v40, v61
	v_fma_f32 v58, v46, v46, v58
	v_fma_f32 v59, v42, v42, v59
	v_fma_f32 v58, v47, v47, v58
	v_fma_f32 v59, v43, v43, v59
	v_mul_f32_e32 v62, v37, v37
	v_mul_f32_e32 v63, v33, v33
	v_add_f32_e32 v58, v58, v59
	v_fma_f32 v60, v36, v36, v62
	v_fma_f32 v61, v32, v32, v63
	v_fma_f32 v60, v38, v38, v60
	v_fma_f32 v61, v34, v34, v61
	v_mov_b32_e32 v63, v35
	v_fma_f32 v60, v39, v39, v60
	v_fma_f32 v61, v35, v35, v61
	v_lshl_add_u64 v[56:57], v[132:133], 0, v[56:57]
	v_add_f32_e32 v58, v58, v60
	v_add_f32_e32 v58, v58, v61
	ds_bpermute_b32 v59, v228, v58
	v_pk_add_f32 v[60:61], v[20:21], 1.0 op_sel_hi:[1,0]
	s_waitcnt lgkmcnt(0)
	v_add_f32_e32 v58, v58, v59
	ds_bpermute_b32 v59, v229, v58
	s_waitcnt lgkmcnt(0)
	v_add_f32_e32 v58, v58, v59
	s_nop 1
	v_add_f32_dpp v58, v58, v58 row_ror:8 row_mask:0xf bank_mask:0xf
	s_nop 1
	v_add_f32_dpp v58, v58, v58 row_ror:4 row_mask:0xf bank_mask:0xf
	s_nop 1
	v_add_f32_dpp v58, v58, v58 quad_perm:[2,3,0,1] row_mask:0xf bank_mask:0xf
	s_nop 1
	v_add_f32_dpp v58, v58, v58 quad_perm:[1,0,3,2] row_mask:0xf bank_mask:0xf
	v_fmamk_f32 v58, v58, 0x3a800000, v234
	v_rsq_f32_e32 v62, v58
	v_pk_add_f32 v[58:59], v[22:23], 1.0 op_sel_hi:[1,0]
	v_pk_mul_f32 v[46:47], v[46:47], v[62:63] op_sel_hi:[1,0]
	v_pk_mul_f32 v[44:45], v[44:45], v[62:63] op_sel_hi:[1,0]
	v_pk_mul_f32 v[46:47], v[10:11], v[46:47]
	v_pk_mul_f32 v[44:45], v[8:9], v[44:45]
	v_pk_fma_f32 v[46:47], v[58:59], v[46:47], v[18:19]
	v_pk_fma_f32 v[44:45], v[60:61], v[44:45], v[16:17]
	v_pk_mul_f32 v[42:43], v[42:43], v[62:63] op_sel_hi:[1,0]
	v_cvt_pk_bf16_f32 v44, v44, v45
	v_cvt_pk_bf16_f32 v45, v46, v47
	v_pk_mul_f32 v[40:41], v[40:41], v[62:63] op_sel_hi:[1,0]
	global_store_dwordx2 v[56:57], v[44:45], off
	v_pk_mul_f32 v[40:41], v[0:1], v[40:41]
	v_pk_mul_f32 v[42:43], v[2:3], v[42:43]
	v_pk_add_f32 v[44:45], v[30:31], 1.0 op_sel_hi:[1,0]
	v_pk_add_f32 v[46:47], v[28:29], 1.0 op_sel_hi:[1,0]
	v_pk_fma_f32 v[42:43], v[44:45], v[42:43], v[26:27]
	v_pk_fma_f32 v[40:41], v[46:47], v[40:41], v[24:25]
	v_pk_mul_f32 v[38:39], v[38:39], v[62:63] op_sel_hi:[1,0]
	v_cvt_pk_bf16_f32 v40, v40, v41
	v_cvt_pk_bf16_f32 v41, v42, v43
	v_pk_mul_f32 v[36:37], v[36:37], v[62:63] op_sel_hi:[1,0]
	global_store_dwordx2 v[56:57], v[40:41], off offset:512
	v_pk_mul_f32 v[36:37], v[4:5], v[36:37]
	v_pk_mul_f32 v[38:39], v[6:7], v[38:39]
	v_pk_add_f32 v[40:41], v[54:55], 1.0 op_sel_hi:[1,0]
	v_pk_add_f32 v[42:43], v[52:53], 1.0 op_sel_hi:[1,0]
	v_pk_fma_f32 v[38:39], v[40:41], v[38:39], v[50:51]
	v_pk_fma_f32 v[36:37], v[42:43], v[36:37], v[48:49]
	v_pk_mul_f32 v[34:35], v[34:35], v[62:63] op_sel_hi:[1,0]
	v_cvt_pk_bf16_f32 v36, v36, v37
	v_cvt_pk_bf16_f32 v37, v38, v39
	v_pk_mul_f32 v[32:33], v[32:33], v[62:63] op_sel_hi:[1,0]
	global_store_dwordx2 v[56:57], v[36:37], off offset:1024
	v_pk_mul_f32 v[32:33], v[12:13], v[32:33]
	v_pk_mul_f32 v[34:35], v[14:15], v[34:35]
	v_pk_add_f32 v[36:37], v[78:79], 1.0 op_sel_hi:[1,0]
	v_pk_add_f32 v[38:39], v[76:77], 1.0 op_sel_hi:[1,0]
	v_pk_fma_f32 v[34:35], v[36:37], v[34:35], v[74:75]
	v_pk_fma_f32 v[32:33], v[38:39], v[32:33], v[72:73]
	s_nop 0
	v_cvt_pk_bf16_f32 v32, v32, v33
	v_cvt_pk_bf16_f32 v33, v34, v35
	global_store_dwordx2 v[56:57], v[32:33], off offset:1536

.LBB0_1142:
	s_or_b64 exec, exec, s[6:7]
	v_mul_f32_e32 v236, v217, v217
	v_mul_f32_e32 v237, v213, v213
	v_fma_f32 v222, v216, v216, v236
	v_fma_f32 v223, v212, v212, v237
	v_fma_f32 v222, v218, v218, v222
	v_fma_f32 v223, v214, v214, v223
	v_fma_f32 v222, v219, v219, v222
	v_fma_f32 v223, v215, v215, v223
	v_mul_f32_e32 v238, v209, v209
	v_mul_f32_e32 v239, v205, v205
	v_add_f32_e32 v129, v222, v223
	v_fma_f32 v236, v208, v208, v238
	v_fma_f32 v237, v204, v204, v239
	v_fma_f32 v236, v210, v210, v236
	v_fma_f32 v237, v206, v206, v237
	v_mov_b32_e32 v239, v207
	v_fma_f32 v236, v211, v211, v236
	v_fma_f32 v237, v207, v207, v237
	v_pk_add_f32 v[222:223], v[20:21], 1.0 op_sel_hi:[1,0]
	v_add_f32_e32 v129, v129, v236
	v_add_f32_e32 v129, v129, v237
	ds_bpermute_b32 v155, v228, v129
	v_lshl_add_u64 v[236:237], v[132:133], 0, v[220:221]
	v_pk_add_f32 v[220:221], v[22:23], 1.0 op_sel_hi:[1,0]
	s_waitcnt lgkmcnt(0)
	v_add_f32_e32 v129, v129, v155
	ds_bpermute_b32 v155, v229, v129
	s_waitcnt lgkmcnt(0)
	v_add_f32_e32 v129, v129, v155
	s_nop 1
	v_add_f32_dpp v129, v129, v129 row_ror:8 row_mask:0xf bank_mask:0xf
	s_nop 1
	v_add_f32_dpp v129, v129, v129 row_ror:4 row_mask:0xf bank_mask:0xf
	s_nop 1
	v_add_f32_dpp v129, v129, v129 quad_perm:[2,3,0,1] row_mask:0xf bank_mask:0xf
	s_nop 1
	v_add_f32_dpp v129, v129, v129 quad_perm:[1,0,3,2] row_mask:0xf bank_mask:0xf
	v_fmamk_f32 v129, v129, 0x3a800000, v234
	v_rsq_f32_e32 v129, v129
	s_nop 0
	v_mov_b32_e32 v238, v129
	v_pk_mul_f32 v[218:219], v[218:219], v[238:239] op_sel_hi:[1,0]
	v_pk_mul_f32 v[216:217], v[216:217], v[238:239] op_sel_hi:[1,0]
	v_pk_mul_f32 v[218:219], v[10:11], v[218:219]
	v_pk_mul_f32 v[216:217], v[8:9], v[216:217]
	v_pk_fma_f32 v[218:219], v[220:221], v[218:219], v[18:19]
	v_pk_fma_f32 v[216:217], v[222:223], v[216:217], v[16:17]
	v_pk_mul_f32 v[214:215], v[214:215], v[238:239] op_sel_hi:[1,0]
	v_cvt_pk_bf16_f32 v216, v216, v217
	v_cvt_pk_bf16_f32 v217, v218, v219
	v_pk_mul_f32 v[212:213], v[212:213], v[238:239] op_sel_hi:[1,0]
	global_store_dwordx2 v[236:237], v[216:217], off
	v_pk_mul_f32 v[216:217], v[0:1], v[212:213]
	v_pk_mul_f32 v[218:219], v[2:3], v[214:215]
	v_pk_add_f32 v[212:213], v[30:31], 1.0 op_sel_hi:[1,0]
	v_pk_add_f32 v[214:215], v[28:29], 1.0 op_sel_hi:[1,0]
	v_pk_fma_f32 v[218:219], v[212:213], v[218:219], v[26:27]
	v_pk_fma_f32 v[216:217], v[214:215], v[216:217], v[24:25]
	v_pk_mul_f32 v[210:211], v[210:211], v[238:239] op_sel_hi:[1,0]
	v_cvt_pk_bf16_f32 v216, v216, v217
	v_cvt_pk_bf16_f32 v217, v218, v219
	v_pk_mul_f32 v[208:209], v[208:209], v[238:239] op_sel_hi:[1,0]
	global_store_dwordx2 v[236:237], v[216:217], off offset:512
	v_pk_mul_f32 v[216:217], v[4:5], v[208:209]
	v_pk_mul_f32 v[218:219], v[6:7], v[210:211]
	v_pk_add_f32 v[208:209], v[54:55], 1.0 op_sel_hi:[1,0]
	v_pk_add_f32 v[210:211], v[52:53], 1.0 op_sel_hi:[1,0]
	v_pk_fma_f32 v[218:219], v[208:209], v[218:219], v[50:51]
	v_pk_fma_f32 v[216:217], v[210:211], v[216:217], v[48:49]
	v_pk_mul_f32 v[206:207], v[206:207], v[238:239] op_sel_hi:[1,0]
	v_cvt_pk_bf16_f32 v216, v216, v217
	v_cvt_pk_bf16_f32 v217, v218, v219
	v_pk_mul_f32 v[204:205], v[204:205], v[238:239] op_sel_hi:[1,0]
	global_store_dwordx2 v[236:237], v[216:217], off offset:1024
	v_pk_mul_f32 v[216:217], v[12:13], v[204:205]
	v_pk_mul_f32 v[218:219], v[14:15], v[206:207]
	v_pk_add_f32 v[204:205], v[78:79], 1.0 op_sel_hi:[1,0]
	v_pk_add_f32 v[206:207], v[76:77], 1.0 op_sel_hi:[1,0]
	v_pk_fma_f32 v[218:219], v[204:205], v[218:219], v[74:75]
	v_pk_fma_f32 v[216:217], v[206:207], v[216:217], v[72:73]
	v_cmp_lt_i32_e32 vcc, v194, v226
	v_cvt_pk_bf16_f32 v216, v216, v217
	v_cvt_pk_bf16_f32 v217, v218, v219
	global_store_dwordx2 v[236:237], v[216:217], off offset:1536
	s_and_saveexec_b64 s[6:7], vcc
	s_cbranch_execz .LBB0_1167
	s_waitcnt vmcnt(43)
	v_lshlrev_b32_e32 v216, 16, v202
	v_and_b32_e32 v217, 0xffff0000, v202
	v_lshlrev_b32_e32 v202, 16, v203
	v_and_b32_e32 v203, 0xffff0000, v203
	v_pk_add_f32 v[126:127], v[126:127], v[202:203]
	s_waitcnt vmcnt(42)
	v_lshlrev_b32_e32 v202, 16, v200
	v_and_b32_e32 v203, 0xffff0000, v200
	v_lshlrev_b32_e32 v200, 16, v201
	v_and_b32_e32 v201, 0xffff0000, v201
	v_pk_add_f32 v[122:123], v[122:123], v[200:201]
	s_waitcnt vmcnt(41)
	v_lshlrev_b32_e32 v200, 16, v198
	v_and_b32_e32 v201, 0xffff0000, v198
	v_lshlrev_b32_e32 v198, 16, v199
	v_and_b32_e32 v199, 0xffff0000, v199
	v_ashrrev_i32_e32 v195, 31, v194
	v_pk_add_f32 v[124:125], v[124:125], v[216:217]
	v_pk_add_f32 v[118:119], v[118:119], v[198:199]
	s_waitcnt vmcnt(40)
	v_lshlrev_b32_e32 v198, 16, v196
	v_and_b32_e32 v199, 0xffff0000, v196
	v_lshlrev_b32_e32 v196, 16, v197
	v_and_b32_e32 v197, 0xffff0000, v197
	v_add_u32_e32 v129, 0xffffe001, v128
	v_lshlrev_b64 v[194:195], 11, v[194:195]
	v_pk_add_f32 v[120:121], v[120:121], v[202:203]
	v_pk_add_f32 v[114:115], v[114:115], v[196:197]
	v_pk_add_f32 v[112:113], v[112:113], v[198:199]
	v_ashrrev_i32_e32 v129, 10, v129
	v_lshl_add_u64 v[196:197], v[134:135], 0, v[194:195]
	v_cvt_pk_bf16_f32 v198, v124, v125
	v_cvt_pk_bf16_f32 v199, v126, v127
	v_pk_add_f32 v[116:117], v[116:117], v[200:201]
	v_add_u32_e32 v129, 1, v129
	v_cmp_lt_i32_e32 vcc, s29, v128
	global_store_dwordx2 v[196:197], v[198:199], off
	v_cvt_pk_bf16_f32 v198, v120, v121
	v_cvt_pk_bf16_f32 v199, v122, v123
	v_cndmask_b32_e32 v129, 0, v129, vcc
	global_store_dwordx2 v[196:197], v[198:199], off offset:512
	v_cvt_pk_bf16_f32 v198, v116, v117
	v_cvt_pk_bf16_f32 v199, v118, v119
	global_store_dwordx2 v[196:197], v[198:199], off offset:1024
	v_cvt_pk_bf16_f32 v198, v112, v113
	v_cvt_pk_bf16_f32 v199, v114, v115
	v_cmp_ne_u32_e32 vcc, v129, v235
	global_store_dwordx2 v[196:197], v[198:199], off offset:1536
	s_and_saveexec_b64 s[40:41], vcc
	s_cbranch_execz .LBB0_1153
	global_load_dwordx4 v[16:19], v[136:137], off
	global_load_dwordx4 v[20:23], v[138:139], off
	v_mad_i64_i32 v[196:197], s[42:43], v129, s16, v[152:153]
	s_mov_b64 s[42:43], 0

.LBB0_1153:
	s_or_b64 exec, exec, s[40:41]
	v_mul_f32_e32 v198, v125, v125
	v_mul_f32_e32 v199, v121, v121
	v_fma_f32 v196, v124, v124, v198
	v_fma_f32 v197, v120, v120, v199
	v_fma_f32 v196, v126, v126, v196
	v_fma_f32 v197, v122, v122, v197
	v_fma_f32 v196, v127, v127, v196
	v_fma_f32 v197, v123, v123, v197
	v_mul_f32_e32 v200, v117, v117
	v_mul_f32_e32 v201, v113, v113
	v_add_f32_e32 v129, v196, v197
	v_fma_f32 v198, v116, v116, v200
	v_fma_f32 v199, v112, v112, v201
	v_fma_f32 v198, v118, v118, v198
	v_fma_f32 v199, v114, v114, v199
	v_mov_b32_e32 v200, v119
	v_mov_b32_e32 v201, v115
	v_fma_f32 v198, v119, v119, v198
	v_fma_f32 v199, v115, v115, v199
	v_lshl_add_u64 v[194:195], v[132:133], 0, v[194:195]
	v_add_f32_e32 v129, v129, v198
	v_add_f32_e32 v129, v129, v199
	ds_bpermute_b32 v155, v228, v129
	s_waitcnt lgkmcnt(0)
	v_add_f32_e32 v129, v129, v155
	ds_bpermute_b32 v155, v229, v129
	s_waitcnt lgkmcnt(0)
	v_add_f32_e32 v129, v129, v155
	s_nop 1
	v_add_f32_dpp v129, v129, v129 row_ror:8 row_mask:0xf bank_mask:0xf
	s_nop 1
	v_add_f32_dpp v129, v129, v129 row_ror:4 row_mask:0xf bank_mask:0xf
	s_nop 1
	v_add_f32_dpp v129, v129, v129 quad_perm:[2,3,0,1] row_mask:0xf bank_mask:0xf
	s_nop 1
	v_add_f32_dpp v129, v129, v129 quad_perm:[1,0,3,2] row_mask:0xf bank_mask:0xf
	v_fmamk_f32 v129, v129, 0x3a800000, v234
	v_rsq_f32_e32 v129, v129
	s_nop 0
	v_mov_b32_e32 v196, v129
	v_pk_mul_f32 v[126:127], v[126:127], v[196:197] op_sel_hi:[1,0]
	v_pk_mul_f32 v[124:125], v[124:125], v[196:197] op_sel_hi:[1,0]
	v_pk_mul_f32 v[122:123], v[122:123], v[196:197] op_sel_hi:[1,0]
	v_pk_mul_f32 v[120:121], v[120:121], v[196:197] op_sel_hi:[1,0]
	v_pk_mul_f32 v[118:119], v[118:119], v[196:197] op_sel_hi:[1,0]
	v_pk_mul_f32 v[116:117], v[116:117], v[196:197] op_sel_hi:[1,0]
	v_pk_mul_f32 v[114:115], v[114:115], v[196:197] op_sel_hi:[1,0]
	v_pk_mul_f32 v[112:113], v[112:113], v[196:197] op_sel_hi:[1,0]
	v_pk_mul_f32 v[124:125], v[8:9], v[124:125]
	v_pk_mul_f32 v[126:127], v[10:11], v[126:127]
	v_pk_mul_f32 v[120:121], v[0:1], v[120:121]
	v_pk_mul_f32 v[122:123], v[2:3], v[122:123]
	v_pk_mul_f32 v[116:117], v[4:5], v[116:117]
	v_pk_mul_f32 v[118:119], v[6:7], v[118:119]
	v_pk_mul_f32 v[112:113], v[12:13], v[112:113]
	v_pk_mul_f32 v[114:115], v[14:15], v[114:115]
	v_pk_fma_f32 v[126:127], v[220:221], v[126:127], v[18:19]
	v_pk_fma_f32 v[124:125], v[222:223], v[124:125], v[16:17]
	v_pk_fma_f32 v[122:123], v[212:213], v[122:123], v[26:27]
	v_pk_fma_f32 v[120:121], v[214:215], v[120:121], v[24:25]
	v_pk_fma_f32 v[118:119], v[208:209], v[118:119], v[50:51]
	v_pk_fma_f32 v[116:117], v[210:211], v[116:117], v[48:49]
	v_pk_fma_f32 v[114:115], v[204:205], v[114:115], v[74:75]
	v_pk_fma_f32 v[112:113], v[206:207], v[112:113], v[72:73]
	v_cvt_pk_bf16_f32 v124, v124, v125
	v_cvt_pk_bf16_f32 v125, v126, v127
	v_cvt_pk_bf16_f32 v120, v120, v121
	v_cvt_pk_bf16_f32 v121, v122, v123
	v_cvt_pk_bf16_f32 v116, v116, v117
	v_cvt_pk_bf16_f32 v117, v118, v119
	v_cvt_pk_bf16_f32 v112, v112, v113
	v_cvt_pk_bf16_f32 v113, v114, v115
	global_store_dwordx2 v[194:195], v[124:125], off
	global_store_dwordx2 v[194:195], v[120:121], off offset:512
	global_store_dwordx2 v[194:195], v[116:117], off offset:1024
	global_store_dwordx2 v[194:195], v[112:113], off offset:1536
	s_or_b64 exec, exec, s[6:7]
	v_cmp_lt_i32_e32 vcc, v184, v226
	s_and_saveexec_b64 s[6:7], vcc
	s_cbranch_execnz .LBB0_1168

.LBB0_1165:
	s_or_b64 exec, exec, s[40:41]
	v_mul_f32_e32 v100, v93, v93
	v_mul_f32_e32 v101, v89, v89
	v_fma_f32 v98, v92, v92, v100
	v_fma_f32 v99, v88, v88, v101
	v_fma_f32 v98, v94, v94, v98
	v_fma_f32 v99, v90, v90, v99
	v_fma_f32 v98, v95, v95, v98
	v_fma_f32 v99, v91, v91, v99
	v_mul_f32_e32 v102, v85, v85
	v_mul_f32_e32 v103, v81, v81
	v_add_f32_e32 v98, v98, v99
	v_fma_f32 v100, v84, v84, v102
	v_fma_f32 v101, v80, v80, v103
	v_fma_f32 v100, v86, v86, v100
	v_fma_f32 v101, v82, v82, v101
	v_mov_b32_e32 v103, v83
	v_fma_f32 v100, v87, v87, v100
	v_fma_f32 v101, v83, v83, v101
	v_lshl_add_u64 v[96:97], v[132:133], 0, v[96:97]
	v_add_f32_e32 v98, v98, v100
	v_add_f32_e32 v98, v98, v101
	ds_bpermute_b32 v99, v228, v98
	v_pk_add_f32 v[100:101], v[20:21], 1.0 op_sel_hi:[1,0]
	s_waitcnt lgkmcnt(0)
	v_add_f32_e32 v98, v98, v99
	ds_bpermute_b32 v99, v229, v98
	s_waitcnt lgkmcnt(0)
	v_add_f32_e32 v98, v98, v99
	s_nop 1
	v_add_f32_dpp v98, v98, v98 row_ror:8 row_mask:0xf bank_mask:0xf
	s_nop 1
	v_add_f32_dpp v98, v98, v98 row_ror:4 row_mask:0xf bank_mask:0xf
	s_nop 1
	v_add_f32_dpp v98, v98, v98 quad_perm:[2,3,0,1] row_mask:0xf bank_mask:0xf
	s_nop 1
	v_add_f32_dpp v98, v98, v98 quad_perm:[1,0,3,2] row_mask:0xf bank_mask:0xf
	v_fmamk_f32 v98, v98, 0x3a800000, v234
	v_rsq_f32_e32 v102, v98
	v_pk_add_f32 v[98:99], v[22:23], 1.0 op_sel_hi:[1,0]
	v_pk_mul_f32 v[94:95], v[94:95], v[102:103] op_sel_hi:[1,0]
	v_pk_mul_f32 v[92:93], v[92:93], v[102:103] op_sel_hi:[1,0]
	v_pk_mul_f32 v[94:95], v[10:11], v[94:95]
	v_pk_mul_f32 v[92:93], v[8:9], v[92:93]
	v_pk_fma_f32 v[94:95], v[98:99], v[94:95], v[18:19]
	v_pk_fma_f32 v[92:93], v[100:101], v[92:93], v[16:17]
	v_pk_mul_f32 v[90:91], v[90:91], v[102:103] op_sel_hi:[1,0]
	v_cvt_pk_bf16_f32 v92, v92, v93
	v_cvt_pk_bf16_f32 v93, v94, v95
	v_pk_mul_f32 v[88:89], v[88:89], v[102:103] op_sel_hi:[1,0]
	global_store_dwordx2 v[96:97], v[92:93], off
	v_pk_mul_f32 v[88:89], v[0:1], v[88:89]
	v_pk_mul_f32 v[90:91], v[2:3], v[90:91]
	v_pk_add_f32 v[92:93], v[30:31], 1.0 op_sel_hi:[1,0]
	v_pk_add_f32 v[94:95], v[28:29], 1.0 op_sel_hi:[1,0]
	v_pk_fma_f32 v[90:91], v[92:93], v[90:91], v[26:27]
	v_pk_fma_f32 v[88:89], v[94:95], v[88:89], v[24:25]
	v_pk_mul_f32 v[86:87], v[86:87], v[102:103] op_sel_hi:[1,0]
	v_cvt_pk_bf16_f32 v88, v88, v89
	v_cvt_pk_bf16_f32 v89, v90, v91
	v_pk_mul_f32 v[84:85], v[84:85], v[102:103] op_sel_hi:[1,0]
	global_store_dwordx2 v[96:97], v[88:89], off offset:512
	v_pk_mul_f32 v[84:85], v[4:5], v[84:85]
	v_pk_mul_f32 v[86:87], v[6:7], v[86:87]
	v_pk_add_f32 v[88:89], v[54:55], 1.0 op_sel_hi:[1,0]
	v_pk_add_f32 v[90:91], v[52:53], 1.0 op_sel_hi:[1,0]
	v_pk_fma_f32 v[86:87], v[88:89], v[86:87], v[50:51]
	v_pk_fma_f32 v[84:85], v[90:91], v[84:85], v[48:49]
	v_pk_mul_f32 v[82:83], v[82:83], v[102:103] op_sel_hi:[1,0]
	v_cvt_pk_bf16_f32 v84, v84, v85
	v_cvt_pk_bf16_f32 v85, v86, v87
	v_pk_mul_f32 v[80:81], v[80:81], v[102:103] op_sel_hi:[1,0]
	global_store_dwordx2 v[96:97], v[84:85], off offset:1024
	v_pk_mul_f32 v[80:81], v[12:13], v[80:81]
	v_pk_mul_f32 v[82:83], v[14:15], v[82:83]
	v_pk_add_f32 v[84:85], v[78:79], 1.0 op_sel_hi:[1,0]
	v_pk_add_f32 v[86:87], v[76:77], 1.0 op_sel_hi:[1,0]
	v_pk_fma_f32 v[82:83], v[84:85], v[82:83], v[74:75]
	v_pk_fma_f32 v[80:81], v[86:87], v[80:81], v[72:73]
	s_nop 0
	v_cvt_pk_bf16_f32 v80, v80, v81
	v_cvt_pk_bf16_f32 v81, v82, v83
	global_store_dwordx2 v[96:97], v[80:81], off offset:1536
	s_or_b64 exec, exec, s[6:7]
	v_cmp_lt_i32_e32 vcc, v164, v226
	s_and_saveexec_b64 s[6:7], vcc
	s_cbranch_execnz .LBB0_1180

.LBB0_1178:
	s_or_b64 exec, exec, s[40:41]
	v_mul_f32_e32 v116, v109, v109
	v_mul_f32_e32 v117, v105, v105
	v_fma_f32 v114, v108, v108, v116
	v_fma_f32 v115, v104, v104, v117
	v_fma_f32 v114, v110, v110, v114
	v_fma_f32 v115, v106, v106, v115
	v_fma_f32 v114, v111, v111, v114
	v_fma_f32 v115, v107, v107, v115
	v_mul_f32_e32 v118, v101, v101
	v_mul_f32_e32 v119, v97, v97
	v_add_f32_e32 v114, v114, v115
	v_fma_f32 v116, v100, v100, v118
	v_fma_f32 v117, v96, v96, v119
	v_fma_f32 v116, v102, v102, v116
	v_fma_f32 v117, v98, v98, v117
	v_mov_b32_e32 v119, v99
	v_fma_f32 v116, v103, v103, v116
	v_fma_f32 v117, v99, v99, v117
	v_lshl_add_u64 v[112:113], v[132:133], 0, v[112:113]
	v_add_f32_e32 v114, v114, v116
	v_add_f32_e32 v114, v114, v117
	ds_bpermute_b32 v115, v228, v114
	v_pk_add_f32 v[116:117], v[20:21], 1.0 op_sel_hi:[1,0]
	s_waitcnt lgkmcnt(0)
	v_add_f32_e32 v114, v114, v115
	ds_bpermute_b32 v115, v229, v114
	s_waitcnt lgkmcnt(0)
	v_add_f32_e32 v114, v114, v115
	s_nop 1
	v_add_f32_dpp v114, v114, v114 row_ror:8 row_mask:0xf bank_mask:0xf
	s_nop 1
	v_add_f32_dpp v114, v114, v114 row_ror:4 row_mask:0xf bank_mask:0xf
	s_nop 1
	v_add_f32_dpp v114, v114, v114 quad_perm:[2,3,0,1] row_mask:0xf bank_mask:0xf
	s_nop 1
	v_add_f32_dpp v114, v114, v114 quad_perm:[1,0,3,2] row_mask:0xf bank_mask:0xf
	v_fmamk_f32 v114, v114, 0x3a800000, v234
	v_rsq_f32_e32 v118, v114
	v_pk_add_f32 v[114:115], v[22:23], 1.0 op_sel_hi:[1,0]
	v_pk_mul_f32 v[110:111], v[110:111], v[118:119] op_sel_hi:[1,0]
	v_pk_mul_f32 v[108:109], v[108:109], v[118:119] op_sel_hi:[1,0]
	v_pk_mul_f32 v[110:111], v[10:11], v[110:111]
	v_pk_mul_f32 v[108:109], v[8:9], v[108:109]
	v_pk_fma_f32 v[110:111], v[114:115], v[110:111], v[18:19]
	v_pk_fma_f32 v[108:109], v[116:117], v[108:109], v[16:17]
	v_pk_mul_f32 v[106:107], v[106:107], v[118:119] op_sel_hi:[1,0]
	v_cvt_pk_bf16_f32 v108, v108, v109
	v_cvt_pk_bf16_f32 v109, v110, v111
	v_pk_mul_f32 v[104:105], v[104:105], v[118:119] op_sel_hi:[1,0]
	global_store_dwordx2 v[112:113], v[108:109], off
	v_pk_mul_f32 v[104:105], v[0:1], v[104:105]
	v_pk_mul_f32 v[106:107], v[2:3], v[106:107]
	v_pk_add_f32 v[108:109], v[30:31], 1.0 op_sel_hi:[1,0]
	v_pk_add_f32 v[110:111], v[28:29], 1.0 op_sel_hi:[1,0]
	v_pk_fma_f32 v[106:107], v[108:109], v[106:107], v[26:27]
	v_pk_fma_f32 v[104:105], v[110:111], v[104:105], v[24:25]
	v_pk_mul_f32 v[102:103], v[102:103], v[118:119] op_sel_hi:[1,0]
	v_cvt_pk_bf16_f32 v104, v104, v105
	v_cvt_pk_bf16_f32 v105, v106, v107
	v_pk_mul_f32 v[100:101], v[100:101], v[118:119] op_sel_hi:[1,0]
	global_store_dwordx2 v[112:113], v[104:105], off offset:512
	v_pk_mul_f32 v[100:101], v[4:5], v[100:101]
	v_pk_mul_f32 v[102:103], v[6:7], v[102:103]
	v_pk_add_f32 v[104:105], v[54:55], 1.0 op_sel_hi:[1,0]
	v_pk_add_f32 v[106:107], v[52:53], 1.0 op_sel_hi:[1,0]
	v_pk_fma_f32 v[102:103], v[104:105], v[102:103], v[50:51]
	v_pk_fma_f32 v[100:101], v[106:107], v[100:101], v[48:49]
	v_pk_mul_f32 v[98:99], v[98:99], v[118:119] op_sel_hi:[1,0]
	v_cvt_pk_bf16_f32 v100, v100, v101
	v_cvt_pk_bf16_f32 v101, v102, v103
	v_pk_mul_f32 v[96:97], v[96:97], v[118:119] op_sel_hi:[1,0]
	global_store_dwordx2 v[112:113], v[100:101], off offset:1024
	v_pk_mul_f32 v[96:97], v[12:13], v[96:97]
	v_pk_mul_f32 v[98:99], v[14:15], v[98:99]
	v_pk_add_f32 v[100:101], v[78:79], 1.0 op_sel_hi:[1,0]
	v_pk_add_f32 v[102:103], v[76:77], 1.0 op_sel_hi:[1,0]
	v_pk_fma_f32 v[98:99], v[100:101], v[98:99], v[74:75]
	v_pk_fma_f32 v[96:97], v[102:103], v[96:97], v[72:73]
	s_nop 0
	v_cvt_pk_bf16_f32 v96, v96, v97
	v_cvt_pk_bf16_f32 v97, v98, v99
	global_store_dwordx2 v[112:113], v[96:97], off offset:1536
	s_or_b64 exec, exec, s[6:7]
	v_cmp_lt_i32_e32 vcc, v174, v226
	s_and_saveexec_b64 s[6:7], vcc
	s_cbranch_execnz .LBB0_1155

.LBB0_1190:
	s_or_b64 exec, exec, s[40:41]
	v_mul_f32_e32 v84, v69, v69
	v_mul_f32_e32 v85, v65, v65
	v_fma_f32 v82, v68, v68, v84
	v_fma_f32 v83, v64, v64, v85
	v_fma_f32 v82, v70, v70, v82
	v_fma_f32 v83, v66, v66, v83
	v_fma_f32 v82, v71, v71, v82
	v_fma_f32 v83, v67, v67, v83
	v_mul_f32_e32 v86, v61, v61
	v_mul_f32_e32 v87, v57, v57
	v_add_f32_e32 v82, v82, v83
	v_fma_f32 v84, v60, v60, v86
	v_fma_f32 v85, v56, v56, v87
	v_fma_f32 v84, v62, v62, v84
	v_fma_f32 v85, v58, v58, v85
	v_mov_b32_e32 v87, v59
	v_fma_f32 v84, v63, v63, v84
	v_fma_f32 v85, v59, v59, v85
	v_lshl_add_u64 v[80:81], v[132:133], 0, v[80:81]
	v_add_f32_e32 v82, v82, v84
	v_add_f32_e32 v82, v82, v85
	ds_bpermute_b32 v83, v228, v82
	v_pk_add_f32 v[84:85], v[20:21], 1.0 op_sel_hi:[1,0]
	s_waitcnt lgkmcnt(0)
	v_add_f32_e32 v82, v82, v83
	ds_bpermute_b32 v83, v229, v82
	s_waitcnt lgkmcnt(0)
	v_add_f32_e32 v82, v82, v83
	s_nop 1
	v_add_f32_dpp v82, v82, v82 row_ror:8 row_mask:0xf bank_mask:0xf
	s_nop 1
	v_add_f32_dpp v82, v82, v82 row_ror:4 row_mask:0xf bank_mask:0xf
	s_nop 1
	v_add_f32_dpp v82, v82, v82 quad_perm:[2,3,0,1] row_mask:0xf bank_mask:0xf
	s_nop 1
	v_add_f32_dpp v82, v82, v82 quad_perm:[1,0,3,2] row_mask:0xf bank_mask:0xf
	v_fmamk_f32 v82, v82, 0x3a800000, v234
	v_rsq_f32_e32 v86, v82
	v_pk_add_f32 v[82:83], v[22:23], 1.0 op_sel_hi:[1,0]
	v_pk_mul_f32 v[70:71], v[70:71], v[86:87] op_sel_hi:[1,0]
	v_pk_mul_f32 v[68:69], v[68:69], v[86:87] op_sel_hi:[1,0]
	v_pk_mul_f32 v[70:71], v[10:11], v[70:71]
	v_pk_mul_f32 v[68:69], v[8:9], v[68:69]
	v_pk_fma_f32 v[70:71], v[82:83], v[70:71], v[18:19]
	v_pk_fma_f32 v[68:69], v[84:85], v[68:69], v[16:17]
	v_pk_mul_f32 v[66:67], v[66:67], v[86:87] op_sel_hi:[1,0]
	v_cvt_pk_bf16_f32 v68, v68, v69
	v_cvt_pk_bf16_f32 v69, v70, v71
	v_pk_mul_f32 v[64:65], v[64:65], v[86:87] op_sel_hi:[1,0]
	global_store_dwordx2 v[80:81], v[68:69], off
	v_pk_mul_f32 v[64:65], v[0:1], v[64:65]
	v_pk_mul_f32 v[66:67], v[2:3], v[66:67]
	v_pk_add_f32 v[68:69], v[30:31], 1.0 op_sel_hi:[1,0]
	v_pk_add_f32 v[70:71], v[28:29], 1.0 op_sel_hi:[1,0]
	v_pk_fma_f32 v[66:67], v[68:69], v[66:67], v[26:27]
	v_pk_fma_f32 v[64:65], v[70:71], v[64:65], v[24:25]
	v_pk_mul_f32 v[62:63], v[62:63], v[86:87] op_sel_hi:[1,0]
	v_cvt_pk_bf16_f32 v64, v64, v65
	v_cvt_pk_bf16_f32 v65, v66, v67
	v_pk_mul_f32 v[60:61], v[60:61], v[86:87] op_sel_hi:[1,0]
	global_store_dwordx2 v[80:81], v[64:65], off offset:512
	v_pk_mul_f32 v[60:61], v[4:5], v[60:61]
	v_pk_mul_f32 v[62:63], v[6:7], v[62:63]
	v_pk_add_f32 v[64:65], v[54:55], 1.0 op_sel_hi:[1,0]
	v_pk_add_f32 v[66:67], v[52:53], 1.0 op_sel_hi:[1,0]
	v_pk_fma_f32 v[62:63], v[64:65], v[62:63], v[50:51]
	v_pk_fma_f32 v[60:61], v[66:67], v[60:61], v[48:49]
	v_pk_mul_f32 v[58:59], v[58:59], v[86:87] op_sel_hi:[1,0]
	v_cvt_pk_bf16_f32 v60, v60, v61
	v_cvt_pk_bf16_f32 v61, v62, v63
	v_pk_mul_f32 v[56:57], v[56:57], v[86:87] op_sel_hi:[1,0]
	global_store_dwordx2 v[80:81], v[60:61], off offset:1024
	v_pk_mul_f32 v[56:57], v[12:13], v[56:57]
	v_pk_mul_f32 v[58:59], v[14:15], v[58:59]
	v_pk_add_f32 v[60:61], v[78:79], 1.0 op_sel_hi:[1,0]
	v_pk_add_f32 v[62:63], v[76:77], 1.0 op_sel_hi:[1,0]
	v_pk_fma_f32 v[58:59], v[60:61], v[58:59], v[74:75]
	v_pk_fma_f32 v[56:57], v[62:63], v[56:57], v[72:73]
	s_nop 0
	v_cvt_pk_bf16_f32 v56, v56, v57
	v_cvt_pk_bf16_f32 v57, v58, v59
	global_store_dwordx2 v[80:81], v[56:57], off offset:1536
	s_or_b64 exec, exec, s[6:7]
	v_cmp_lt_i32_e32 vcc, v154, v226
	s_and_saveexec_b64 s[6:7], vcc
	s_cbranch_execz .LBB0_1131

.LBB0_1559:
	v_add_u32_e32 v35, s90, v128
	s_waitcnt vmcnt(6)
	v_add_co_u32_e32 v36, vcc, s10, v24
	s_waitcnt vmcnt(4)
	v_min_i32_e32 v38, 0x2fff, v35
	v_addc_co_u32_e32 v37, vcc, -1, v25, vcc
	global_load_dwordx2 v[130:131], v[24:25], off
	global_load_dwordx2 v[132:133], v[36:37], off
	v_ashrrev_i32_e32 v39, 31, v38
	v_lshlrev_b64 v[38:39], 11, v[38:39]
	v_lshl_add_u64 v[40:41], v[16:17], 0, v[38:39]
	v_lshl_add_u64 v[38:39], v[18:19], 0, v[38:39]
	global_load_dwordx2 v[134:135], v[24:25], off offset:-512
	global_load_dwordx2 v[136:137], v[36:37], off offset:-512
	global_load_dwordx2 v[106:107], v[40:41], off
	global_load_dwordx2 v[110:111], v[40:41], off offset:512
	global_load_dwordx2 v[114:115], v[40:41], off offset:1024
	global_load_dwordx2 v[118:119], v[40:41], off offset:1536
	global_load_dwordx2 v[108:109], v[38:39], off
	global_load_dwordx2 v[112:113], v[38:39], off offset:512
	global_load_dwordx2 v[116:117], v[38:39], off offset:1024
	global_load_dwordx2 v[120:121], v[38:39], off offset:1536
	global_load_dwordx2 v[138:139], v[24:25], off offset:-1024
	global_load_dwordx2 v[140:141], v[36:37], off offset:-1024
	v_add_u32_e32 v88, s90, v129
	v_min_i32_e32 v38, 0x2fff, v88
	v_ashrrev_i32_e32 v39, 31, v38
	v_lshlrev_b64 v[38:39], 11, v[38:39]
	v_lshl_add_u64 v[40:41], v[16:17], 0, v[38:39]
	v_lshl_add_u64 v[38:39], v[18:19], 0, v[38:39]
	global_load_dwordx2 v[142:143], v[24:25], off offset:-1536
	global_load_dwordx2 v[102:103], v[40:41], off
	global_load_dwordx2 v[98:99], v[40:41], off offset:512
	global_load_dwordx2 v[94:95], v[40:41], off offset:1024
	global_load_dwordx2 v[90:91], v[40:41], off offset:1536
	global_load_dwordx2 v[144:145], v[36:37], off offset:-1536
	global_load_dwordx2 v[104:105], v[38:39], off
	global_load_dwordx2 v[100:101], v[38:39], off offset:512
	global_load_dwordx2 v[96:97], v[38:39], off offset:1024
	global_load_dwordx2 v[92:93], v[38:39], off offset:1536
	v_add_u32_e32 v70, s90, v30
	v_min_i32_e32 v36, 0x2fff, v70
	v_ashrrev_i32_e32 v37, 31, v36
	v_lshlrev_b64 v[36:37], 11, v[36:37]
	v_lshl_add_u64 v[38:39], v[16:17], 0, v[36:37]
	v_lshl_add_u64 v[36:37], v[18:19], 0, v[36:37]
	v_add_u32_e32 v52, s90, v29
	global_load_dwordx2 v[84:85], v[38:39], off
	global_load_dwordx2 v[80:81], v[38:39], off offset:512
	global_load_dwordx2 v[76:77], v[38:39], off offset:1024
	global_load_dwordx2 v[72:73], v[38:39], off offset:1536
	global_load_dwordx2 v[86:87], v[36:37], off
	global_load_dwordx2 v[82:83], v[36:37], off offset:512
	global_load_dwordx2 v[78:79], v[36:37], off offset:1024
	global_load_dwordx2 v[74:75], v[36:37], off offset:1536
	v_min_i32_e32 v36, 0x2fff, v52
	v_ashrrev_i32_e32 v37, 31, v36
	v_lshlrev_b64 v[36:37], 11, v[36:37]
	v_lshl_add_u64 v[38:39], v[16:17], 0, v[36:37]
	v_lshl_add_u64 v[36:37], v[18:19], 0, v[36:37]
	v_add_u32_e32 v34, s90, v28
	global_load_dwordx2 v[66:67], v[38:39], off
	global_load_dwordx2 v[62:63], v[38:39], off offset:512
	global_load_dwordx2 v[58:59], v[38:39], off offset:1024
	global_load_dwordx2 v[54:55], v[38:39], off offset:1536
	global_load_dwordx2 v[68:69], v[36:37], off
	global_load_dwordx2 v[64:65], v[36:37], off offset:512
	global_load_dwordx2 v[60:61], v[36:37], off offset:1024
	global_load_dwordx2 v[56:57], v[36:37], off offset:1536
	v_min_i32_e32 v36, 0x2fff, v34
	v_ashrrev_i32_e32 v37, 31, v36
	v_lshlrev_b64 v[36:37], 11, v[36:37]
	v_lshl_add_u64 v[38:39], v[16:17], 0, v[36:37]
	v_lshl_add_u64 v[146:147], v[18:19], 0, v[36:37]
	global_load_dwordx2 v[48:49], v[38:39], off
	global_load_dwordx2 v[44:45], v[38:39], off offset:512
	global_load_dwordx2 v[40:41], v[38:39], off offset:1024
	global_load_dwordx2 v[36:37], v[38:39], off offset:1536
	global_load_dwordx2 v[50:51], v[146:147], off
	global_load_dwordx2 v[46:47], v[146:147], off offset:512
	global_load_dwordx2 v[42:43], v[146:147], off offset:1024
	s_nop 0
	global_load_dwordx2 v[38:39], v[146:147], off offset:1536
	s_waitcnt vmcnt(47)
	v_lshlrev_b32_e32 v146, 16, v130
	v_and_b32_e32 v147, 0xffff0000, v130
	v_lshlrev_b32_e32 v130, 16, v131
	v_and_b32_e32 v131, 0xffff0000, v131
	s_waitcnt vmcnt(46)
	v_lshlrev_b32_e32 v148, 16, v132
	v_and_b32_e32 v149, 0xffff0000, v132
	v_lshlrev_b32_e32 v132, 16, v133
	v_and_b32_e32 v133, 0xffff0000, v133
	v_pk_add_f32 v[150:151], v[130:131], v[132:133]
	s_waitcnt vmcnt(45)
	v_lshlrev_b32_e32 v130, 16, v134
	v_and_b32_e32 v131, 0xffff0000, v134
	v_lshlrev_b32_e32 v132, 16, v135
	v_and_b32_e32 v133, 0xffff0000, v135
	s_waitcnt vmcnt(44)
	v_lshlrev_b32_e32 v134, 16, v136
	v_and_b32_e32 v135, 0xffff0000, v136
	v_lshlrev_b32_e32 v136, 16, v137
	v_and_b32_e32 v137, 0xffff0000, v137
	v_pk_add_f32 v[136:137], v[132:133], v[136:137]
	v_pk_add_f32 v[134:135], v[130:131], v[134:135]
	s_waitcnt vmcnt(35)
	v_lshlrev_b32_e32 v130, 16, v138
	v_and_b32_e32 v131, 0xffff0000, v138
	v_lshlrev_b32_e32 v132, 16, v139
	v_and_b32_e32 v133, 0xffff0000, v139
	s_waitcnt vmcnt(34)
	v_lshlrev_b32_e32 v138, 16, v140
	v_and_b32_e32 v139, 0xffff0000, v140
	v_lshlrev_b32_e32 v140, 16, v141
	v_and_b32_e32 v141, 0xffff0000, v141
	v_pk_add_f32 v[140:141], v[132:133], v[140:141]
	v_pk_add_f32 v[138:139], v[130:131], v[138:139]
	s_waitcnt vmcnt(33)
	v_lshlrev_b32_e32 v130, 16, v142
	v_and_b32_e32 v131, 0xffff0000, v142
	v_lshlrev_b32_e32 v132, 16, v143
	v_and_b32_e32 v133, 0xffff0000, v143
	s_waitcnt vmcnt(28)
	v_lshlrev_b32_e32 v142, 16, v144
	v_and_b32_e32 v143, 0xffff0000, v144
	v_lshlrev_b32_e32 v144, 16, v145
	v_and_b32_e32 v145, 0xffff0000, v145
	v_pk_add_f32 v[130:131], v[130:131], v[142:143]
	v_pk_add_f32 v[132:133], v[132:133], v[144:145]
	v_mul_f32_e32 v144, v139, v139
	v_mul_f32_e32 v145, v131, v131
	v_pk_add_f32 v[146:147], v[146:147], v[148:149]
	v_fma_f32 v142, v138, v138, v144
	v_fma_f32 v143, v130, v130, v145
	v_fma_f32 v142, v140, v140, v142
	v_fma_f32 v143, v132, v132, v143
	v_fma_f32 v142, v141, v141, v142
	v_fma_f32 v143, v133, v133, v143
	v_mul_f32_e32 v148, v147, v147
	v_mul_f32_e32 v149, v135, v135
	v_add_f32_e32 v53, v142, v143
	v_fma_f32 v144, v146, v146, v148
	v_fma_f32 v145, v134, v134, v149
	v_fma_f32 v144, v150, v150, v144
	v_fma_f32 v145, v136, v136, v145
	v_mov_b32_e32 v148, v151
	v_mov_b32_e32 v149, v137
	v_fma_f32 v144, v151, v151, v144
	v_fma_f32 v145, v137, v137, v145
	s_nop 0
	v_add_f32_e32 v53, v145, v53
	v_add_f32_e32 v53, v144, v53
	ds_bpermute_b32 v71, v122, v53
	v_lshl_add_u64 v[144:145], v[32:33], 0, v[22:23]
	s_waitcnt lgkmcnt(0)
	v_add_f32_e32 v53, v53, v71
	ds_bpermute_b32 v71, v123, v53
	s_waitcnt lgkmcnt(0)
	v_add_f32_e32 v53, v53, v71
	s_nop 1
	v_add_f32_dpp v53, v53, v53 row_ror:8 row_mask:0xf bank_mask:0xf
	s_nop 1
	v_add_f32_dpp v53, v53, v53 row_ror:4 row_mask:0xf bank_mask:0xf
	s_nop 1
	v_add_f32_dpp v53, v53, v53 quad_perm:[2,3,0,1] row_mask:0xf bank_mask:0xf
	s_nop 1
	v_add_f32_dpp v53, v53, v53 quad_perm:[1,0,3,2] row_mask:0xf bank_mask:0xf
	v_fmamk_f32 v53, v53, 0x3a800000, v31
	v_rsq_f32_e32 v53, v53
	s_nop 0
	v_mov_b32_e32 v142, v53
	v_pk_mul_f32 v[130:131], v[130:131], v[142:143] op_sel_hi:[1,0]
	v_pk_mul_f32 v[132:133], v[132:133], v[142:143] op_sel_hi:[1,0]
	v_pk_mul_f32 v[130:131], v[0:1], v[130:131]
	v_pk_mul_f32 v[132:133], v[2:3], v[132:133]
	global_store_dwordx4 v[144:145], v[130:133], off nt
	v_cmp_gt_i32_e32 vcc, s8, v35
	s_nop 0
	v_pk_mul_f32 v[130:131], v[138:139], v[142:143] op_sel_hi:[1,0]
	v_pk_mul_f32 v[132:133], v[140:141], v[142:143] op_sel_hi:[1,0]
	v_pk_mul_f32 v[130:131], v[4:5], v[130:131]
	v_pk_mul_f32 v[132:133], v[6:7], v[132:133]
	global_store_dwordx4 v[144:145], v[130:133], off offset:1024 nt
	s_nop 1
	v_pk_mul_f32 v[130:131], v[134:135], v[142:143] op_sel_hi:[1,0]
	v_pk_mul_f32 v[132:133], v[136:137], v[142:143] op_sel_hi:[1,0]
	v_pk_mul_f32 v[130:131], v[8:9], v[130:131]
	v_pk_mul_f32 v[132:133], v[10:11], v[132:133]
	global_store_dwordx4 v[144:145], v[130:133], off offset:2048 nt
	s_nop 1
	v_pk_mul_f32 v[130:131], v[146:147], v[142:143] op_sel_hi:[1,0]
	v_pk_mul_f32 v[132:133], v[150:151], v[142:143] op_sel_hi:[1,0]
	v_pk_mul_f32 v[130:131], v[12:13], v[130:131]
	v_pk_mul_f32 v[132:133], v[14:15], v[132:133]
	global_store_dwordx4 v[144:145], v[130:133], off offset:3072 nt
	s_and_saveexec_b64 s[6:7], vcc
	s_cbranch_execz .LBB0_1561
	v_lshlrev_b32_e32 v130, 16, v118
	v_and_b32_e32 v131, 0xffff0000, v118
	v_lshlrev_b32_e32 v118, 16, v119
	v_and_b32_e32 v119, 0xffff0000, v119
	v_lshlrev_b32_e32 v132, 16, v120
	v_and_b32_e32 v133, 0xffff0000, v120
	v_lshlrev_b32_e32 v120, 16, v121
	v_and_b32_e32 v121, 0xffff0000, v121
	v_pk_add_f32 v[118:119], v[118:119], v[120:121]
	v_pk_add_f32 v[120:121], v[130:131], v[132:133]
	v_lshlrev_b32_e32 v130, 16, v114
	v_and_b32_e32 v131, 0xffff0000, v114
	v_lshlrev_b32_e32 v114, 16, v115
	v_and_b32_e32 v115, 0xffff0000, v115
	v_lshlrev_b32_e32 v132, 16, v116
	v_and_b32_e32 v133, 0xffff0000, v116
	v_lshlrev_b32_e32 v116, 16, v117
	v_and_b32_e32 v117, 0xffff0000, v117
	v_pk_add_f32 v[114:115], v[114:115], v[116:117]
	v_pk_add_f32 v[116:117], v[130:131], v[132:133]
	v_lshlrev_b32_e32 v130, 16, v110
	v_and_b32_e32 v131, 0xffff0000, v110
	v_lshlrev_b32_e32 v110, 16, v111
	v_and_b32_e32 v111, 0xffff0000, v111
	v_lshlrev_b32_e32 v132, 16, v112
	v_and_b32_e32 v133, 0xffff0000, v112
	v_lshlrev_b32_e32 v112, 16, v113
	v_and_b32_e32 v113, 0xffff0000, v113
	v_pk_add_f32 v[110:111], v[110:111], v[112:113]
	v_pk_add_f32 v[112:113], v[130:131], v[132:133]
	v_lshlrev_b32_e32 v130, 16, v106
	v_and_b32_e32 v131, 0xffff0000, v106
	v_lshlrev_b32_e32 v106, 16, v107
	v_and_b32_e32 v107, 0xffff0000, v107
	v_lshlrev_b32_e32 v132, 16, v108
	v_and_b32_e32 v133, 0xffff0000, v108
	v_lshlrev_b32_e32 v108, 16, v109
	v_and_b32_e32 v109, 0xffff0000, v109
	v_pk_add_f32 v[106:107], v[106:107], v[108:109]
	v_pk_add_f32 v[108:109], v[130:131], v[132:133]
	v_mul_f32_e32 v132, v109, v109
	v_mul_f32_e32 v133, v113, v113
	v_fma_f32 v130, v108, v108, v132
	v_fma_f32 v131, v112, v112, v133
	v_fma_f32 v130, v106, v106, v130
	v_fma_f32 v131, v110, v110, v131
	v_fma_f32 v130, v107, v107, v130
	v_fma_f32 v131, v111, v111, v131
	v_mul_f32_e32 v134, v117, v117
	v_mul_f32_e32 v135, v121, v121
	v_add_f32_e32 v53, v130, v131
	v_fma_f32 v132, v116, v116, v134
	v_fma_f32 v133, v120, v120, v135
	v_fma_f32 v132, v114, v114, v132
	v_fma_f32 v133, v118, v118, v133
	v_fma_f32 v132, v115, v115, v132
	v_fma_f32 v133, v119, v119, v133
	s_nop 0
	v_add_f32_e32 v53, v53, v132
	v_add_f32_e32 v53, v53, v133
	ds_bpermute_b32 v71, v122, v53
	v_lshl_add_u64 v[132:133], v[32:33], 0, v[26:27]
	s_waitcnt lgkmcnt(0)
	v_add_f32_e32 v53, v53, v71
	ds_bpermute_b32 v71, v123, v53
	s_waitcnt lgkmcnt(0)
	v_add_f32_e32 v53, v53, v71
	s_nop 1
	v_add_f32_dpp v53, v53, v53 row_ror:8 row_mask:0xf bank_mask:0xf
	s_nop 1
	v_add_f32_dpp v53, v53, v53 row_ror:4 row_mask:0xf bank_mask:0xf
	s_nop 1
	v_add_f32_dpp v53, v53, v53 quad_perm:[2,3,0,1] row_mask:0xf bank_mask:0xf
	s_nop 1
	v_add_f32_dpp v53, v53, v53 quad_perm:[1,0,3,2] row_mask:0xf bank_mask:0xf
	v_fmamk_f32 v53, v53, 0x3a800000, v31
	v_rsq_f32_e32 v53, v53
	s_nop 0
	v_mov_b32_e32 v130, v53
	v_pk_mul_f32 v[134:135], v[108:109], v[130:131] op_sel_hi:[1,0]
	v_pk_mul_f32 v[106:107], v[106:107], v[130:131] op_sel_hi:[1,0]
	s_nop 0
	v_pk_mul_f32 v[108:109], v[2:3], v[106:107]
	v_pk_mul_f32 v[106:107], v[0:1], v[134:135]
	global_store_dwordx4 v[132:133], v[106:109], off nt
	s_nop 1
	v_pk_mul_f32 v[106:107], v[112:113], v[130:131] op_sel_hi:[1,0]
	v_pk_mul_f32 v[108:109], v[110:111], v[130:131] op_sel_hi:[1,0]
	v_pk_mul_f32 v[106:107], v[4:5], v[106:107]
	v_pk_mul_f32 v[108:109], v[6:7], v[108:109]
	global_store_dwordx4 v[132:133], v[106:109], off offset:1024 nt
	s_nop 1
	v_pk_mul_f32 v[106:107], v[116:117], v[130:131] op_sel_hi:[1,0]
	v_pk_mul_f32 v[108:109], v[114:115], v[130:131] op_sel_hi:[1,0]
	v_pk_mul_f32 v[106:107], v[8:9], v[106:107]
	v_pk_mul_f32 v[108:109], v[10:11], v[108:109]
	global_store_dwordx4 v[132:133], v[106:109], off offset:2048 nt
	s_nop 1
	v_pk_mul_f32 v[106:107], v[120:121], v[130:131] op_sel_hi:[1,0]
	v_pk_mul_f32 v[108:109], v[118:119], v[130:131] op_sel_hi:[1,0]
	v_pk_mul_f32 v[106:107], v[12:13], v[106:107]
	v_pk_mul_f32 v[108:109], v[14:15], v[108:109]
	global_store_dwordx4 v[132:133], v[106:109], off offset:3072 nt
.LBB0_1561:
	s_or_b64 exec, exec, s[6:7]
	v_add_u32_e32 v35, s33, v35
	v_cmp_gt_i32_e32 vcc, s8, v35
	s_and_saveexec_b64 s[6:7], vcc
	s_cbranch_execz .LBB0_1563
	s_waitcnt vmcnt(31)
	v_lshlrev_b32_e32 v106, 16, v104
	v_and_b32_e32 v107, 0xffff0000, v104
	v_lshlrev_b32_e32 v104, 16, v105
	v_and_b32_e32 v105, 0xffff0000, v105
	v_lshlrev_b32_e32 v108, 16, v102
	v_and_b32_e32 v109, 0xffff0000, v102
	v_lshlrev_b32_e32 v102, 16, v103
	v_and_b32_e32 v103, 0xffff0000, v103
	v_pk_add_f32 v[102:103], v[102:103], v[104:105]
	v_pk_add_f32 v[104:105], v[108:109], v[106:107]
	s_waitcnt vmcnt(30)
	v_lshlrev_b32_e32 v106, 16, v100
	v_and_b32_e32 v107, 0xffff0000, v100
	v_lshlrev_b32_e32 v100, 16, v101
	v_and_b32_e32 v101, 0xffff0000, v101
	v_lshlrev_b32_e32 v108, 16, v98
	v_and_b32_e32 v109, 0xffff0000, v98
	v_lshlrev_b32_e32 v98, 16, v99
	v_and_b32_e32 v99, 0xffff0000, v99
	v_pk_add_f32 v[98:99], v[98:99], v[100:101]
	v_pk_add_f32 v[100:101], v[108:109], v[106:107]
	s_waitcnt vmcnt(29)
	v_lshlrev_b32_e32 v106, 16, v96
	v_and_b32_e32 v107, 0xffff0000, v96
	v_lshlrev_b32_e32 v96, 16, v97
	v_and_b32_e32 v97, 0xffff0000, v97
	v_lshlrev_b32_e32 v108, 16, v94
	v_and_b32_e32 v109, 0xffff0000, v94
	v_lshlrev_b32_e32 v94, 16, v95
	v_and_b32_e32 v95, 0xffff0000, v95
	v_pk_add_f32 v[94:95], v[94:95], v[96:97]
	v_pk_add_f32 v[96:97], v[108:109], v[106:107]
	s_waitcnt vmcnt(28)
	v_lshlrev_b32_e32 v106, 16, v92
	v_and_b32_e32 v107, 0xffff0000, v92
	v_lshlrev_b32_e32 v108, 16, v90
	v_and_b32_e32 v109, 0xffff0000, v90
	v_lshlrev_b32_e32 v92, 16, v93
	v_and_b32_e32 v93, 0xffff0000, v93
	v_lshlrev_b32_e32 v90, 16, v91
	v_and_b32_e32 v91, 0xffff0000, v91
	v_pk_add_f32 v[106:107], v[108:109], v[106:107]
	v_pk_add_f32 v[92:93], v[90:91], v[92:93]
	v_mul_f32_e32 v108, v105, v105
	v_mul_f32_e32 v109, v101, v101
	v_fma_f32 v90, v104, v104, v108
	v_fma_f32 v91, v100, v100, v109
	v_fma_f32 v90, v102, v102, v90
	v_fma_f32 v91, v98, v98, v91
	v_fma_f32 v90, v103, v103, v90
	v_fma_f32 v91, v99, v99, v91
	v_mul_f32_e32 v110, v97, v97
	v_mul_f32_e32 v111, v107, v107
	v_add_f32_e32 v53, v90, v91
	v_fma_f32 v108, v96, v96, v110
	v_fma_f32 v109, v106, v106, v111
	v_fma_f32 v108, v94, v94, v108
	v_fma_f32 v109, v92, v92, v109
	v_fma_f32 v108, v95, v95, v108
	v_fma_f32 v109, v93, v93, v109
	v_ashrrev_i32_e32 v89, 31, v88
	v_add_f32_e32 v53, v53, v108
	v_add_f32_e32 v53, v53, v109
	ds_bpermute_b32 v71, v122, v53
	v_lshlrev_b64 v[88:89], 12, v[88:89]
	v_lshl_add_u64 v[110:111], v[20:21], 0, v[88:89]
	s_waitcnt lgkmcnt(0)
	v_add_f32_e32 v53, v53, v71
	ds_bpermute_b32 v71, v123, v53
	s_waitcnt lgkmcnt(0)
	v_add_f32_e32 v53, v53, v71
	s_nop 1
	v_add_f32_dpp v53, v53, v53 row_ror:8 row_mask:0xf bank_mask:0xf
	s_nop 1
	v_add_f32_dpp v53, v53, v53 row_ror:4 row_mask:0xf bank_mask:0xf
	s_nop 1
	v_add_f32_dpp v53, v53, v53 quad_perm:[2,3,0,1] row_mask:0xf bank_mask:0xf
	s_nop 1
	v_add_f32_dpp v53, v53, v53 quad_perm:[1,0,3,2] row_mask:0xf bank_mask:0xf
	v_fmamk_f32 v53, v53, 0x3a800000, v31
	v_rsq_f32_e32 v53, v53
	s_nop 0
	v_mov_b32_e32 v108, v53
	v_pk_mul_f32 v[88:89], v[104:105], v[108:109] op_sel_hi:[1,0]
	v_pk_mul_f32 v[90:91], v[102:103], v[108:109] op_sel_hi:[1,0]
	v_pk_mul_f32 v[88:89], v[0:1], v[88:89]
	v_pk_mul_f32 v[90:91], v[2:3], v[90:91]
	global_store_dwordx4 v[110:111], v[88:91], off nt
	s_nop 1
	v_pk_mul_f32 v[88:89], v[100:101], v[108:109] op_sel_hi:[1,0]
	v_pk_mul_f32 v[90:91], v[98:99], v[108:109] op_sel_hi:[1,0]
	v_pk_mul_f32 v[88:89], v[4:5], v[88:89]
	v_pk_mul_f32 v[90:91], v[6:7], v[90:91]
	global_store_dwordx4 v[110:111], v[88:91], off offset:1024 nt
	s_nop 1
	v_pk_mul_f32 v[88:89], v[96:97], v[108:109] op_sel_hi:[1,0]
	v_pk_mul_f32 v[90:91], v[94:95], v[108:109] op_sel_hi:[1,0]
	v_pk_mul_f32 v[88:89], v[8:9], v[88:89]
	v_pk_mul_f32 v[90:91], v[10:11], v[90:91]
	global_store_dwordx4 v[110:111], v[88:91], off offset:2048 nt
	s_nop 1
	v_pk_mul_f32 v[88:89], v[106:107], v[108:109] op_sel_hi:[1,0]
	v_pk_mul_f32 v[90:91], v[92:93], v[108:109] op_sel_hi:[1,0]
	v_pk_mul_f32 v[88:89], v[12:13], v[88:89]
	v_pk_mul_f32 v[90:91], v[14:15], v[90:91]
	global_store_dwordx4 v[110:111], v[88:91], off offset:3072 nt
.LBB0_1563:
	s_or_b64 exec, exec, s[6:7]
	v_add_u32_e32 v35, s33, v35
	v_cmp_gt_i32_e32 vcc, s8, v35
	s_and_saveexec_b64 s[6:7], vcc
	s_cbranch_execz .LBB0_1565
	s_waitcnt vmcnt(23)
	v_lshlrev_b32_e32 v88, 16, v86
	v_and_b32_e32 v89, 0xffff0000, v86
	v_lshlrev_b32_e32 v86, 16, v87
	v_and_b32_e32 v87, 0xffff0000, v87
	v_lshlrev_b32_e32 v90, 16, v84
	v_and_b32_e32 v91, 0xffff0000, v84
	v_lshlrev_b32_e32 v84, 16, v85
	v_and_b32_e32 v85, 0xffff0000, v85
	v_pk_add_f32 v[84:85], v[84:85], v[86:87]
	v_pk_add_f32 v[86:87], v[90:91], v[88:89]
	s_waitcnt vmcnt(22)
	v_lshlrev_b32_e32 v88, 16, v82
	v_and_b32_e32 v89, 0xffff0000, v82
	v_lshlrev_b32_e32 v82, 16, v83
	v_and_b32_e32 v83, 0xffff0000, v83
	v_lshlrev_b32_e32 v90, 16, v80
	v_and_b32_e32 v91, 0xffff0000, v80
	v_lshlrev_b32_e32 v80, 16, v81
	v_and_b32_e32 v81, 0xffff0000, v81
	v_pk_add_f32 v[80:81], v[80:81], v[82:83]
	v_pk_add_f32 v[82:83], v[90:91], v[88:89]
	s_waitcnt vmcnt(21)
	v_lshlrev_b32_e32 v88, 16, v78
	v_and_b32_e32 v89, 0xffff0000, v78
	v_lshlrev_b32_e32 v78, 16, v79
	v_and_b32_e32 v79, 0xffff0000, v79
	v_lshlrev_b32_e32 v90, 16, v76
	v_and_b32_e32 v91, 0xffff0000, v76
	v_lshlrev_b32_e32 v76, 16, v77
	v_and_b32_e32 v77, 0xffff0000, v77
	v_pk_add_f32 v[76:77], v[76:77], v[78:79]
	v_pk_add_f32 v[78:79], v[90:91], v[88:89]
	s_waitcnt vmcnt(20)
	v_lshlrev_b32_e32 v88, 16, v74
	v_and_b32_e32 v89, 0xffff0000, v74
	v_lshlrev_b32_e32 v90, 16, v72
	v_and_b32_e32 v91, 0xffff0000, v72
	v_lshlrev_b32_e32 v74, 16, v75
	v_and_b32_e32 v75, 0xffff0000, v75
	v_lshlrev_b32_e32 v72, 16, v73
	v_and_b32_e32 v73, 0xffff0000, v73
	v_pk_add_f32 v[88:89], v[90:91], v[88:89]
	v_pk_add_f32 v[74:75], v[72:73], v[74:75]
	v_mul_f32_e32 v90, v87, v87
	v_mul_f32_e32 v91, v83, v83
	v_fma_f32 v72, v86, v86, v90
	v_fma_f32 v73, v82, v82, v91
	v_fma_f32 v72, v84, v84, v72
	v_fma_f32 v73, v80, v80, v73
	v_fma_f32 v72, v85, v85, v72
	v_fma_f32 v73, v81, v81, v73
	v_mul_f32_e32 v92, v79, v79
	v_mul_f32_e32 v93, v89, v89
	v_add_f32_e32 v53, v72, v73
	v_fma_f32 v90, v78, v78, v92
	v_fma_f32 v91, v88, v88, v93
	v_fma_f32 v90, v76, v76, v90
	v_fma_f32 v91, v74, v74, v91
	v_fma_f32 v90, v77, v77, v90
	v_fma_f32 v91, v75, v75, v91
	s_nop 0
	v_add_f32_e32 v53, v53, v90
	v_add_f32_e32 v53, v53, v91
	ds_bpermute_b32 v71, v122, v53
	s_waitcnt lgkmcnt(0)
	v_add_f32_e32 v53, v53, v71
	ds_bpermute_b32 v71, v123, v53
	s_waitcnt lgkmcnt(0)
	v_add_f32_e32 v53, v53, v71
	s_nop 1
	v_add_f32_dpp v53, v53, v53 row_ror:8 row_mask:0xf bank_mask:0xf
	s_nop 1
	v_add_f32_dpp v53, v53, v53 row_ror:4 row_mask:0xf bank_mask:0xf
	s_nop 1
	v_add_f32_dpp v53, v53, v53 quad_perm:[2,3,0,1] row_mask:0xf bank_mask:0xf
	s_nop 1
	v_add_f32_dpp v53, v53, v53 quad_perm:[1,0,3,2] row_mask:0xf bank_mask:0xf
	v_fmamk_f32 v53, v53, 0x3a800000, v31
	v_rsq_f32_e32 v53, v53
	v_ashrrev_i32_e32 v71, 31, v70
	v_lshlrev_b64 v[70:71], 12, v[70:71]
	v_lshl_add_u64 v[92:93], v[20:21], 0, v[70:71]
	v_mov_b32_e32 v90, v53
	v_pk_mul_f32 v[70:71], v[86:87], v[90:91] op_sel_hi:[1,0]
	v_pk_mul_f32 v[72:73], v[84:85], v[90:91] op_sel_hi:[1,0]
	v_pk_mul_f32 v[70:71], v[0:1], v[70:71]
	v_pk_mul_f32 v[72:73], v[2:3], v[72:73]
	global_store_dwordx4 v[92:93], v[70:73], off nt
	s_nop 1
	v_pk_mul_f32 v[70:71], v[82:83], v[90:91] op_sel_hi:[1,0]
	v_pk_mul_f32 v[72:73], v[80:81], v[90:91] op_sel_hi:[1,0]
	v_pk_mul_f32 v[70:71], v[4:5], v[70:71]
	v_pk_mul_f32 v[72:73], v[6:7], v[72:73]
	global_store_dwordx4 v[92:93], v[70:73], off offset:1024 nt
	s_nop 1
	v_pk_mul_f32 v[70:71], v[78:79], v[90:91] op_sel_hi:[1,0]
	v_pk_mul_f32 v[72:73], v[76:77], v[90:91] op_sel_hi:[1,0]
	v_pk_mul_f32 v[70:71], v[8:9], v[70:71]
	v_pk_mul_f32 v[72:73], v[10:11], v[72:73]
	global_store_dwordx4 v[92:93], v[70:73], off offset:2048 nt
	s_nop 1
	v_pk_mul_f32 v[70:71], v[88:89], v[90:91] op_sel_hi:[1,0]
	v_pk_mul_f32 v[72:73], v[74:75], v[90:91] op_sel_hi:[1,0]
	v_pk_mul_f32 v[70:71], v[12:13], v[70:71]
	v_pk_mul_f32 v[72:73], v[14:15], v[72:73]
	global_store_dwordx4 v[92:93], v[70:73], off offset:3072 nt
.LBB0_1565:
	s_or_b64 exec, exec, s[6:7]
	v_add_u32_e32 v35, s33, v35
	v_cmp_gt_i32_e32 vcc, s8, v35
	s_and_saveexec_b64 s[6:7], vcc
	s_cbranch_execz .LBB0_1567
	s_waitcnt vmcnt(15)
	v_lshlrev_b32_e32 v70, 16, v68
	v_and_b32_e32 v71, 0xffff0000, v68
	v_lshlrev_b32_e32 v68, 16, v69
	v_and_b32_e32 v69, 0xffff0000, v69
	v_lshlrev_b32_e32 v72, 16, v66
	v_and_b32_e32 v73, 0xffff0000, v66
	v_lshlrev_b32_e32 v66, 16, v67
	v_and_b32_e32 v67, 0xffff0000, v67
	v_pk_add_f32 v[66:67], v[66:67], v[68:69]
	v_pk_add_f32 v[68:69], v[72:73], v[70:71]
	s_waitcnt vmcnt(14)
	v_lshlrev_b32_e32 v70, 16, v64
	v_and_b32_e32 v71, 0xffff0000, v64
	v_lshlrev_b32_e32 v64, 16, v65
	v_and_b32_e32 v65, 0xffff0000, v65
	v_lshlrev_b32_e32 v72, 16, v62
	v_and_b32_e32 v73, 0xffff0000, v62
	v_lshlrev_b32_e32 v62, 16, v63
	v_and_b32_e32 v63, 0xffff0000, v63
	v_pk_add_f32 v[62:63], v[62:63], v[64:65]
	v_pk_add_f32 v[64:65], v[72:73], v[70:71]
	s_waitcnt vmcnt(13)
	v_lshlrev_b32_e32 v70, 16, v60
	v_and_b32_e32 v71, 0xffff0000, v60
	v_lshlrev_b32_e32 v60, 16, v61
	v_and_b32_e32 v61, 0xffff0000, v61
	v_lshlrev_b32_e32 v72, 16, v58
	v_and_b32_e32 v73, 0xffff0000, v58
	v_lshlrev_b32_e32 v58, 16, v59
	v_and_b32_e32 v59, 0xffff0000, v59
	v_pk_add_f32 v[58:59], v[58:59], v[60:61]
	v_pk_add_f32 v[60:61], v[72:73], v[70:71]
	s_waitcnt vmcnt(12)
	v_lshlrev_b32_e32 v70, 16, v56
	v_and_b32_e32 v71, 0xffff0000, v56
	v_lshlrev_b32_e32 v72, 16, v54
	v_and_b32_e32 v73, 0xffff0000, v54
	v_lshlrev_b32_e32 v56, 16, v57
	v_and_b32_e32 v57, 0xffff0000, v57
	v_lshlrev_b32_e32 v54, 16, v55
	v_and_b32_e32 v55, 0xffff0000, v55
	v_pk_add_f32 v[70:71], v[72:73], v[70:71]
	v_pk_add_f32 v[56:57], v[54:55], v[56:57]
	v_mul_f32_e32 v72, v69, v69
	v_mul_f32_e32 v73, v65, v65
	v_fma_f32 v54, v68, v68, v72
	v_fma_f32 v55, v64, v64, v73
	v_fma_f32 v54, v66, v66, v54
	v_fma_f32 v55, v62, v62, v55
	v_fma_f32 v54, v67, v67, v54
	v_fma_f32 v55, v63, v63, v55
	v_mul_f32_e32 v74, v61, v61
	v_mul_f32_e32 v75, v71, v71
	v_add_f32_e32 v53, v54, v55
	v_fma_f32 v72, v60, v60, v74
	v_fma_f32 v73, v70, v70, v75
	v_fma_f32 v72, v58, v58, v72
	v_fma_f32 v73, v56, v56, v73
	v_fma_f32 v72, v59, v59, v72
	v_fma_f32 v73, v57, v57, v73
	s_nop 0
	v_add_f32_e32 v53, v53, v72
	v_add_f32_e32 v53, v53, v73
	ds_bpermute_b32 v54, v122, v53
	s_waitcnt lgkmcnt(0)
	v_add_f32_e32 v53, v53, v54
	ds_bpermute_b32 v54, v123, v53
	s_waitcnt lgkmcnt(0)
	v_add_f32_e32 v53, v53, v54
	s_nop 1
	v_add_f32_dpp v53, v53, v53 row_ror:8 row_mask:0xf bank_mask:0xf
	s_nop 1
	v_add_f32_dpp v53, v53, v53 row_ror:4 row_mask:0xf bank_mask:0xf
	s_nop 1
	v_add_f32_dpp v53, v53, v53 quad_perm:[2,3,0,1] row_mask:0xf bank_mask:0xf
	s_nop 1
	v_add_f32_dpp v53, v53, v53 quad_perm:[1,0,3,2] row_mask:0xf bank_mask:0xf
	v_fmamk_f32 v53, v53, 0x3a800000, v31
	v_rsq_f32_e32 v54, v53
	v_ashrrev_i32_e32 v53, 31, v52
	v_lshlrev_b64 v[52:53], 12, v[52:53]
	v_lshl_add_u64 v[74:75], v[20:21], 0, v[52:53]
	v_mov_b32_e32 v72, v54
	v_pk_mul_f32 v[52:53], v[68:69], v[72:73] op_sel_hi:[1,0]
	v_pk_mul_f32 v[54:55], v[66:67], v[72:73] op_sel_hi:[1,0]
	v_pk_mul_f32 v[52:53], v[0:1], v[52:53]
	v_pk_mul_f32 v[54:55], v[2:3], v[54:55]
	global_store_dwordx4 v[74:75], v[52:55], off nt
	s_nop 1
	v_pk_mul_f32 v[52:53], v[64:65], v[72:73] op_sel_hi:[1,0]
	v_pk_mul_f32 v[54:55], v[62:63], v[72:73] op_sel_hi:[1,0]
	v_pk_mul_f32 v[52:53], v[4:5], v[52:53]
	v_pk_mul_f32 v[54:55], v[6:7], v[54:55]
	global_store_dwordx4 v[74:75], v[52:55], off offset:1024 nt
	s_nop 1
	v_pk_mul_f32 v[52:53], v[60:61], v[72:73] op_sel_hi:[1,0]
	v_pk_mul_f32 v[54:55], v[58:59], v[72:73] op_sel_hi:[1,0]
	v_pk_mul_f32 v[52:53], v[8:9], v[52:53]
	v_pk_mul_f32 v[54:55], v[10:11], v[54:55]
	global_store_dwordx4 v[74:75], v[52:55], off offset:2048 nt
	s_nop 1
	v_pk_mul_f32 v[52:53], v[70:71], v[72:73] op_sel_hi:[1,0]
	v_pk_mul_f32 v[54:55], v[56:57], v[72:73] op_sel_hi:[1,0]
	v_pk_mul_f32 v[52:53], v[12:13], v[52:53]
	v_pk_mul_f32 v[54:55], v[14:15], v[54:55]
	global_store_dwordx4 v[74:75], v[52:55], off offset:3072 nt
.LBB0_1567:
	s_or_b64 exec, exec, s[6:7]
	s_nop 0
	v_add_u32_e32 v52, s33, v35
	v_cmp_gt_i32_e32 vcc, s8, v52
	s_and_saveexec_b64 s[6:7], vcc
	s_cbranch_execz .LBB0_1558
	s_waitcnt vmcnt(7)
	v_lshlrev_b32_e32 v54, 16, v50
	v_and_b32_e32 v55, 0xffff0000, v50
	v_lshlrev_b32_e32 v50, 16, v51
	v_and_b32_e32 v51, 0xffff0000, v51
	v_lshlrev_b32_e32 v56, 16, v48
	v_and_b32_e32 v57, 0xffff0000, v48
	v_lshlrev_b32_e32 v48, 16, v49
	v_and_b32_e32 v49, 0xffff0000, v49
	v_pk_add_f32 v[48:49], v[48:49], v[50:51]
	v_pk_add_f32 v[50:51], v[56:57], v[54:55]
	s_waitcnt vmcnt(6)
	v_lshlrev_b32_e32 v54, 16, v46
	v_and_b32_e32 v55, 0xffff0000, v46
	v_lshlrev_b32_e32 v46, 16, v47
	v_and_b32_e32 v47, 0xffff0000, v47
	v_lshlrev_b32_e32 v56, 16, v44
	v_and_b32_e32 v57, 0xffff0000, v44
	v_lshlrev_b32_e32 v44, 16, v45
	v_and_b32_e32 v45, 0xffff0000, v45
	v_pk_add_f32 v[44:45], v[44:45], v[46:47]
	v_pk_add_f32 v[46:47], v[56:57], v[54:55]
	s_waitcnt vmcnt(5)
	v_lshlrev_b32_e32 v54, 16, v42
	v_and_b32_e32 v55, 0xffff0000, v42
	v_lshlrev_b32_e32 v42, 16, v43
	v_and_b32_e32 v43, 0xffff0000, v43
	v_lshlrev_b32_e32 v56, 16, v40
	v_and_b32_e32 v57, 0xffff0000, v40
	v_lshlrev_b32_e32 v40, 16, v41
	v_and_b32_e32 v41, 0xffff0000, v41
	v_pk_add_f32 v[40:41], v[40:41], v[42:43]
	v_pk_add_f32 v[42:43], v[56:57], v[54:55]
	s_waitcnt vmcnt(4)
	v_lshlrev_b32_e32 v54, 16, v38
	v_and_b32_e32 v55, 0xffff0000, v38
	v_lshlrev_b32_e32 v56, 16, v36
	v_and_b32_e32 v57, 0xffff0000, v36
	v_lshlrev_b32_e32 v38, 16, v39
	v_and_b32_e32 v39, 0xffff0000, v39
	v_lshlrev_b32_e32 v36, 16, v37
	v_and_b32_e32 v37, 0xffff0000, v37
	v_pk_add_f32 v[54:55], v[56:57], v[54:55]
	v_pk_add_f32 v[38:39], v[36:37], v[38:39]
	v_mul_f32_e32 v56, v51, v51
	v_mul_f32_e32 v57, v47, v47
	v_fma_f32 v36, v50, v50, v56
	v_fma_f32 v37, v46, v46, v57
	v_fma_f32 v36, v48, v48, v36
	v_fma_f32 v37, v44, v44, v37
	v_fma_f32 v36, v49, v49, v36
	v_fma_f32 v37, v45, v45, v37
	v_mul_f32_e32 v58, v43, v43
	v_mul_f32_e32 v59, v55, v55
	v_add_f32_e32 v35, v36, v37
	v_fma_f32 v56, v42, v42, v58
	v_fma_f32 v57, v54, v54, v59
	v_fma_f32 v56, v40, v40, v56
	v_fma_f32 v57, v38, v38, v57
	v_fma_f32 v56, v41, v41, v56
	v_fma_f32 v57, v39, v39, v57
	s_nop 0
	v_add_f32_e32 v35, v35, v56
	v_add_f32_e32 v35, v35, v57
	ds_bpermute_b32 v36, v122, v35
	s_waitcnt lgkmcnt(0)
	v_add_f32_e32 v35, v35, v36
	ds_bpermute_b32 v36, v123, v35
	s_waitcnt lgkmcnt(0)
	v_add_f32_e32 v35, v35, v36
	s_nop 1
	v_add_f32_dpp v35, v35, v35 row_ror:8 row_mask:0xf bank_mask:0xf
	s_nop 1
	v_add_f32_dpp v35, v35, v35 row_ror:4 row_mask:0xf bank_mask:0xf
	s_nop 1
	v_add_f32_dpp v35, v35, v35 quad_perm:[2,3,0,1] row_mask:0xf bank_mask:0xf
	s_nop 1
	v_add_f32_dpp v35, v35, v35 quad_perm:[1,0,3,2] row_mask:0xf bank_mask:0xf
	v_fmamk_f32 v35, v35, 0x3a800000, v31
	v_rsq_f32_e32 v36, v35
	v_ashrrev_i32_e32 v35, 31, v34
	v_lshlrev_b64 v[34:35], 12, v[34:35]
	v_lshl_add_u64 v[58:59], v[20:21], 0, v[34:35]
	v_mov_b32_e32 v56, v36
	v_pk_mul_f32 v[34:35], v[50:51], v[56:57] op_sel_hi:[1,0]
	v_pk_mul_f32 v[36:37], v[48:49], v[56:57] op_sel_hi:[1,0]
	v_pk_mul_f32 v[34:35], v[0:1], v[34:35]
	v_pk_mul_f32 v[36:37], v[2:3], v[36:37]
	global_store_dwordx4 v[58:59], v[34:37], off nt
	s_nop 1
	v_pk_mul_f32 v[34:35], v[46:47], v[56:57] op_sel_hi:[1,0]
	v_pk_mul_f32 v[36:37], v[44:45], v[56:57] op_sel_hi:[1,0]
	v_pk_mul_f32 v[34:35], v[4:5], v[34:35]
	v_pk_mul_f32 v[36:37], v[6:7], v[36:37]
	global_store_dwordx4 v[58:59], v[34:37], off offset:1024 nt
	s_nop 1
	v_pk_mul_f32 v[34:35], v[42:43], v[56:57] op_sel_hi:[1,0]
	v_pk_mul_f32 v[36:37], v[40:41], v[56:57] op_sel_hi:[1,0]
	v_pk_mul_f32 v[34:35], v[8:9], v[34:35]
	v_pk_mul_f32 v[36:37], v[10:11], v[36:37]
	global_store_dwordx4 v[58:59], v[34:37], off offset:2048 nt
	s_nop 1
	v_pk_mul_f32 v[34:35], v[54:55], v[56:57] op_sel_hi:[1,0]
	v_pk_mul_f32 v[36:37], v[38:39], v[56:57] op_sel_hi:[1,0]
	v_pk_mul_f32 v[34:35], v[12:13], v[34:35]
	v_pk_mul_f32 v[36:37], v[14:15], v[36:37]
	global_store_dwordx4 v[58:59], v[34:37], off offset:3072 nt
	s_branch .LBB0_1558
